# same as previous plus: f32 residual store issue merged behind the AX store's LDS wait (out-of-line copy for the no-AX path)
# baseline (speedup 1.0000x reference)
; #define LAS __attribute__((address_space(3)))
; __device__ __forceinline__ unsigned cvt_pk_bf16(float lo, float hi) { const cvt_f32x2_t v = {lo, hi}; const cvt_bf16x2_t b = __builtin_convertvector(v, cvt_bf16x2_t); return __builtin_bit_cast(unsigned, b); }
; __device__ __forceinline__ float sq4(f32x4 v) { return (v[0] * v[0] + v[1] * v[1]) + (v[2] * v[2] + v[3] * v[3]); }
;     __device__ __forceinline__ void operator()(const f32x4 (&acc)[2][2][4][2], const Unit& u, int wr, int wc, int fr, int fq) const {
;     ...
; #pragma unroll
;         for (int ai = 0; ai < 2; ++ai) {
;             f32x4 xr[4][2][2];
; #pragma unroll
;             for (int m = 0; m < 4; ++m) { const size_t off = (size_t)(u.pm * 256 + ai * 128 + wr * 64 + m * 16 + fr) * DM + col0;
; #pragma unroll
;                 for (int bj = 0; bj < 2; ++bj)
; #pragma unroll
;                     for (int n = 0; n < 2; ++n) xr[m][bj][n] = *(const f32x4*)(xin + off + 128 * bj + 4 * n); }
;             asm volatile("" ::: "memory");
; #pragma unroll
;             for (int m = 0; m < 4; ++m) {
;                 const int row = u.pm * 256 + ai * 128 + wr * 64 + m * 16 + fr;
;                 const size_t off = (size_t)row * DM + col0;
;                 float ss = 0.f;
; #pragma unroll
;                 for (int bj = 0; bj < 2; ++bj) {
;                     const f32x4 xo0 = xr[m][bj][0] + *(const LAS f32x4*)(gtp + 128 * bj) * acc[ai][bj][m][0], xo1 = xr[m][bj][1] + *(const LAS f32x4*)(gtp + 128 * bj + 4) * acc[ai][bj][m][1];
;                     *(f32x4*)(xout + off + 128 * bj) = xo0; *(f32x4*)(xout + off + 128 * bj + 4) = xo1;
;                     if (gmn) { ss += sq4(xo0) + sq4(xo1); const f32x4 a = xo0 * *(const LAS f32x4*)(gmp + 128 * bj), c = xo1 * *(const LAS f32x4*)(gmp + 128 * bj + 4);
;                         u32x4 w; w.x = cvt_pk_bf16(a[0], a[1]); w.y = cvt_pk_bf16(a[2], a[3]); w.z = cvt_pk_bf16(c[0], c[1]); w.w = cvt_pk_bf16(c[2], c[3]); *(u32x4*)(AX + off + 128 * bj) = w; }
;                 }
;                 if (gmn) { ss += __shfl_xor(ss, 16); ss += __shfl_xor(ss, 32); if (fq == 0) statx[(size_t)row * 16 + u.pn * 4 + wc] = ss; }
.LBB0_216:
	s_or_b64 exec, exec, s[46:47]
	s_or_b32 s44, s44, s58
	v_lshl_add_u32 v224, v250, 3, s44
	s_lshl_b32 s44, s77, 8
	s_add_i32 s44, s44, s7
	v_add_u32_e32 v226, s44, v106
	v_readlane_b32 s44, v255, 46
	v_lshlrev_b32_e32 v104, 5, v250
	v_ashrrev_i32_e32 v225, 31, v224
	v_readlane_b32 s45, v255, 47
	v_ashrrev_i32_e32 v227, 31, v226
	v_add_u32_e32 v249, s87, v104
	v_add_u32_e32 v192, s8, v104
	v_lshl_add_u64 v[228:229], v[224:225], 2, s[44:45]
	v_lshlrev_b64 v[104:105], 12, v[226:227]
	v_add_u32_e32 v234, 16, v226
	s_waitcnt vmcnt(0) lgkmcnt(0)
	s_barrier
	v_lshl_add_u64 v[104:105], v[228:229], 0, v[104:105]
	v_ashrrev_i32_e32 v235, 31, v234
	global_load_dwordx4 v[194:197], v[104:105], off offset:16
	global_load_dwordx4 v[198:201], v[104:105], off
	global_load_dwordx4 v[184:187], v[104:105], off offset:528
	global_load_dwordx4 v[188:191], v[104:105], off offset:512
	v_lshlrev_b64 v[104:105], 12, v[234:235]
	v_add_u32_e32 v232, 32, v226
	v_lshl_add_u64 v[104:105], v[228:229], 0, v[104:105]
	v_ashrrev_i32_e32 v233, 31, v232
	global_load_dwordx4 v[176:179], v[104:105], off offset:16
	global_load_dwordx4 v[180:183], v[104:105], off
	global_load_dwordx4 v[168:171], v[104:105], off offset:528
	global_load_dwordx4 v[172:175], v[104:105], off offset:512
	v_lshlrev_b64 v[104:105], 12, v[232:233]
	v_add_u32_e32 v230, 48, v226
	v_lshl_add_u64 v[104:105], v[228:229], 0, v[104:105]
	v_ashrrev_i32_e32 v231, 31, v230
	global_load_dwordx4 v[160:163], v[104:105], off offset:16
	global_load_dwordx4 v[164:167], v[104:105], off
	global_load_dwordx4 v[152:155], v[104:105], off offset:528
	global_load_dwordx4 v[156:159], v[104:105], off offset:512
	v_lshlrev_b64 v[104:105], 12, v[230:231]
	v_lshl_add_u64 v[112:113], v[228:229], 0, v[104:105]
	global_load_dwordx4 v[136:139], v[112:113], off offset:16
	global_load_dwordx4 v[144:147], v[112:113], off
	global_load_dwordx4 v[104:107], v[112:113], off offset:528
	s_nop 0
	global_load_dwordx4 v[112:115], v[112:113], off offset:512
	v_lshlrev_b64 v[140:141], 10, v[226:227]
	v_lshl_add_u64 v[202:203], v[140:141], 0, v[224:225]
	ds_read_b128 v[148:151], v249
	ds_read_b128 v[140:143], v249 offset:16
	v_lshl_add_u64 v[236:237], v[202:203], 2, s[20:21]
	v_lshl_add_u32 v236, v202, 2, v246
	v_mov_b32_e32 v251, 0
	s_andn2_b64 vcc, exec, s[40:41]
	v_lshl_add_u64 v[238:239], v[202:203], 1, s[16:17]
	v_lshl_add_u64 v[238:239], v[204:205], 0, v[238:239]
	s_waitcnt vmcnt(0) lgkmcnt(0)
	v_pk_fma_f32 v[128:129], v[128:129], v[140:141], v[194:195]
	v_cndmask_b32_e64 v194, 0, 1, s[40:41]
	v_pk_fma_f32 v[134:135], v[134:135], v[150:151], v[200:201]
	v_pk_fma_f32 v[132:133], v[132:133], v[148:149], v[198:199]
	v_pk_fma_f32 v[130:131], v[130:131], v[142:143], v[196:197]
	v_cmp_ne_u32_e64 s[46:47], 1, v194
	ds_write_b128 v208, v[132:135]
	ds_write_b128 v208, v[128:131] offset:16
	ds_read_b128 v[216:219], v210
	ds_read_b128 v[220:223], v210 offset:1152
	s_cbranch_vccnz .Lxn_ph_5262
	v_mov_b32_e32 v196, v133
	v_mov_b32_e32 v197, v129
	v_mov_b32_e32 v194, v132
	v_mov_b32_e32 v195, v128
	v_pk_mul_f32 v[196:197], v[196:197], v[196:197]
	v_mov_b32_e32 v198, v135
	v_mov_b32_e32 v199, v131
	v_pk_fma_f32 v[194:195], v[194:195], v[194:195], v[196:197]
	v_mov_b32_e32 v196, v134
	v_mov_b32_e32 v197, v130
	v_pk_mul_f32 v[198:199], v[198:199], v[198:199]
	s_nop 0
	v_pk_fma_f32 v[196:197], v[196:197], v[196:197], v[198:199]
	s_nop 0
	v_pk_add_f32 v[194:195], v[194:195], v[196:197]
	s_nop 0
	v_add_f32_e32 v251, v194, v195
	ds_read_b128 v[194:197], v192
	ds_read_b128 v[198:201], v192 offset:16
	s_waitcnt lgkmcnt(1)
	v_pk_mul_f32 v[134:135], v[134:135], v[196:197]
	v_pk_mul_f32 v[132:133], v[132:133], v[194:195]
	s_waitcnt lgkmcnt(0)
	v_pk_mul_f32 v[194:195], v[130:131], v[200:201]
	v_pk_mul_f32 v[130:131], v[128:129], v[198:199]
	v_cvt_pk_bf16_f32 v128, v132, v133
	v_cvt_pk_bf16_f32 v129, v134, v135
	v_cvt_pk_bf16_f32 v130, v130, v131
	v_cvt_pk_bf16_f32 v131, v194, v195
	ds_bpermute_b32 v128, v206, v128
	ds_bpermute_b32 v129, v206, v129
	ds_bpermute_b32 v130, v206, v130
	ds_bpermute_b32 v131, v206, v131
	s_waitcnt lgkmcnt(0)
	global_store_dwordx4 v[238:239], v[128:131], off
	s_waitcnt lgkmcnt(0)
	global_store_dwordx4 v236, v[216:219], s[20:21]
	global_store_dwordx4 v236, v[220:223], s[100:101]
.LBB0_218:
	ds_read_b128 v[132:135], v249 offset:512
	ds_read_b128 v[128:131], v249 offset:528
	s_lshl_b32 s76, s76, 2
	v_cmp_eq_u32_e64 s[44:45], 0, v250
	s_ashr_i32 s77, s76, 31
	s_waitcnt lgkmcnt(1)
	v_pk_fma_f32 v[126:127], v[126:127], v[134:135], v[190:191]
	v_pk_fma_f32 v[124:125], v[124:125], v[132:133], v[188:189]
	s_waitcnt lgkmcnt(0)
	v_pk_fma_f32 v[122:123], v[122:123], v[130:131], v[186:187]
	v_pk_fma_f32 v[120:121], v[120:121], v[128:129], v[184:185]
	s_and_b64 vcc, exec, s[46:47]
	ds_write_b128 v208, v[124:127]
	ds_write_b128 v208, v[120:123] offset:16
	ds_read_b128 v[216:219], v210
	ds_read_b128 v[220:223], v210 offset:1152
	s_cbranch_vccnz .Lxn_ph_5309
	ds_read_b128 v[184:187], v192 offset:512
	ds_read_b128 v[188:191], v192 offset:528
	s_waitcnt lgkmcnt(1)
	v_pk_mul_f32 v[184:185], v[124:125], v[184:185]
	s_waitcnt lgkmcnt(0)
	v_pk_mul_f32 v[188:189], v[120:121], v[188:189]
	v_mul_f32_e32 v121, v121, v121
	v_mul_f32_e32 v125, v125, v125
	v_fmac_f32_e32 v121, v120, v120
	v_mul_f32_e32 v120, v123, v123
	v_pk_mul_f32 v[190:191], v[122:123], v[190:191]
	v_fmac_f32_e32 v125, v124, v124
	v_mul_f32_e32 v124, v127, v127
	v_fmac_f32_e32 v120, v122, v122
	v_and_b32_e32 v122, 64, v242
	v_fmac_f32_e32 v124, v126, v126
	v_add_f32_e32 v120, v121, v120
	v_xor_b32_e32 v121, 16, v242
	v_add_u32_e32 v122, 64, v122
	v_add_f32_e32 v124, v125, v124
	v_cmp_lt_i32_e32 vcc, v121, v122
	v_add_f32_e32 v120, v124, v120
	v_add_f32_e32 v120, v251, v120
	v_cndmask_b32_e32 v121, v242, v121, vcc
	v_lshlrev_b32_e32 v121, 2, v121
	ds_bpermute_b32 v121, v121, v120
	v_pk_mul_f32 v[186:187], v[126:127], v[186:187]
	v_cvt_pk_bf16_f32 v184, v184, v185
	v_cvt_pk_bf16_f32 v185, v186, v187
	v_cvt_pk_bf16_f32 v186, v188, v189
	s_waitcnt lgkmcnt(0)
	v_add_f32_e32 v120, v120, v121
	v_xor_b32_e32 v121, 32, v242
	v_cmp_lt_i32_e32 vcc, v121, v122
	v_cvt_pk_bf16_f32 v187, v190, v191
	ds_bpermute_b32 v184, v206, v184
	ds_bpermute_b32 v185, v206, v185
	ds_bpermute_b32 v186, v206, v186
	ds_bpermute_b32 v187, v206, v187
	s_waitcnt lgkmcnt(0)
	global_store_dwordx4 v[238:239], v[184:187], off offset:256
	s_waitcnt lgkmcnt(0)
	global_store_dwordx4 v236, v[216:219], s[20:21] offset:512
	global_store_dwordx4 v236, v[220:223], s[100:101] offset:512
	v_cndmask_b32_e32 v121, v242, v121, vcc
	v_lshlrev_b32_e32 v121, 2, v121
	ds_bpermute_b32 v121, v121, v120
	s_and_saveexec_b64 s[54:55], s[44:45]
	s_cbranch_execz .LBB0_221
	v_lshlrev_b64 v[122:123], 6, v[226:227]
	v_lshl_add_u64 v[122:123], s[22:23], 0, v[122:123]
	v_lshl_add_u64 v[122:123], s[76:77], 2, v[122:123]
	s_lshl_b32 s92, s6, 2
	v_lshl_add_u64 v[122:123], v[122:123], 0, s[92:93]
	s_waitcnt lgkmcnt(0)
	v_add_f32_e32 v120, v120, v121
	global_store_dword v[122:123], v120, off

; #define LAS __attribute__((address_space(3)))
; __device__ __forceinline__ unsigned cvt_pk_bf16(float lo, float hi) { const cvt_f32x2_t v = {lo, hi}; const cvt_bf16x2_t b = __builtin_convertvector(v, cvt_bf16x2_t); return __builtin_bit_cast(unsigned, b); }
; __device__ __forceinline__ float sq4(f32x4 v) { return (v[0] * v[0] + v[1] * v[1]) + (v[2] * v[2] + v[3] * v[3]); }
;     __device__ __forceinline__ void operator()(const f32x4 (&acc)[2][2][4][2], const Unit& u, int wr, int wc, int fr, int fq) const {
;     ...
;             for (int m = 0; m < 4; ++m) {
;                 const int row = u.pm * 256 + ai * 128 + wr * 64 + m * 16 + fr;
;                 const size_t off = (size_t)row * DM + col0;
;                 float ss = 0.f;
; #pragma unroll
;                 for (int bj = 0; bj < 2; ++bj) {
;                     const f32x4 xo0 = xr[m][bj][0] + *(const LAS f32x4*)(gtp + 128 * bj) * acc[ai][bj][m][0], xo1 = xr[m][bj][1] + *(const LAS f32x4*)(gtp + 128 * bj + 4) * acc[ai][bj][m][1];
;                     *(f32x4*)(xout + off + 128 * bj) = xo0; *(f32x4*)(xout + off + 128 * bj + 4) = xo1;
;                     if (gmn) { ss += sq4(xo0) + sq4(xo1); const f32x4 a = xo0 * *(const LAS f32x4*)(gmp + 128 * bj), c = xo1 * *(const LAS f32x4*)(gmp + 128 * bj + 4);
;                         u32x4 w; w.x = cvt_pk_bf16(a[0], a[1]); w.y = cvt_pk_bf16(a[2], a[3]); w.z = cvt_pk_bf16(c[0], c[1]); w.w = cvt_pk_bf16(c[2], c[3]); *(u32x4*)(AX + off + 128 * bj) = w; }
;                 }
;                 if (gmn) { ss += __shfl_xor(ss, 16); ss += __shfl_xor(ss, 32); if (fq == 0) statx[(size_t)row * 16 + u.pn * 4 + wc] = ss; }
.LBB0_222:
	s_waitcnt lgkmcnt(0)
	v_lshlrev_b64 v[120:121], 10, v[234:235]
	v_lshl_add_u64 v[184:185], v[120:121], 0, v[224:225]
	v_pk_fma_f32 v[120:121], v[118:119], v[150:151], v[182:183]
	v_pk_fma_f32 v[118:119], v[116:117], v[148:149], v[180:181]
	v_pk_fma_f32 v[124:125], v[110:111], v[142:143], v[178:179]
	v_pk_fma_f32 v[122:123], v[108:109], v[140:141], v[176:177]
	v_lshl_add_u64 v[126:127], v[184:185], 2, s[20:21]
	v_lshl_add_u32 v126, v184, 2, v246
	s_mov_b64 s[54:55], -1
	s_and_b64 vcc, exec, s[46:47]
	v_pk_fma_f32 v[116:117], v[100:101], v[132:133], v[172:173]
	v_pk_fma_f32 v[108:109], v[92:93], v[128:129], v[168:169]
	ds_write_b128 v208, v[118:121]
	ds_write_b128 v208, v[122:125] offset:16
	ds_read_b128 v[216:219], v210
	ds_read_b128 v[220:223], v210 offset:1152
	s_cbranch_vccnz .Lxn_ph_5378
	v_mul_f32_e32 v92, v119, v119
	v_mul_f32_e32 v93, v121, v121
	ds_read_b128 v[176:179], v192
	ds_read_b128 v[180:183], v192 offset:16
	v_fmac_f32_e32 v92, v118, v118
	v_fmac_f32_e32 v93, v120, v120
	v_add_f32_e32 v92, v92, v93
	v_mul_f32_e32 v93, v123, v123
	v_mul_f32_e32 v100, v125, v125
	v_fmac_f32_e32 v93, v122, v122
	v_fmac_f32_e32 v100, v124, v124
	v_add_f32_e32 v93, v93, v100
	v_add_f32_e32 v172, v92, v93
	s_waitcnt lgkmcnt(1)
	v_pk_mul_f32 v[92:93], v[120:121], v[178:179]
	v_pk_mul_f32 v[100:101], v[118:119], v[176:177]
	s_waitcnt lgkmcnt(0)
	v_pk_mul_f32 v[110:111], v[124:125], v[182:183]
	v_pk_mul_f32 v[120:121], v[122:123], v[180:181]
	v_cvt_pk_bf16_f32 v118, v100, v101
	v_cvt_pk_bf16_f32 v119, v92, v93
	v_cvt_pk_bf16_f32 v120, v120, v121
	v_cvt_pk_bf16_f32 v121, v110, v111
	v_lshl_add_u64 v[92:93], v[184:185], 1, s[16:17]
	ds_bpermute_b32 v118, v206, v118
	ds_bpermute_b32 v119, v206, v119
	ds_bpermute_b32 v120, v206, v120
	ds_bpermute_b32 v121, v206, v121
	s_waitcnt lgkmcnt(0)
	v_lshl_add_u64 v[92:93], v[204:205], 0, v[92:93]
	global_store_dwordx4 v[92:93], v[118:121], off
	s_waitcnt lgkmcnt(0)
	global_store_dwordx4 v126, v[216:219], s[20:21]
	global_store_dwordx4 v126, v[220:223], s[100:101]
	v_pk_fma_f32 v[110:111], v[94:95], v[130:131], v[170:171]
	s_nop 0
	v_pk_fma_f32 v[118:119], v[102:103], v[134:135], v[174:175]
	ds_write_b128 v208, v[116:119]
	ds_write_b128 v208, v[108:111] offset:16
	ds_read_b128 v[216:219], v210
	ds_read_b128 v[220:223], v210 offset:1152
	ds_read_b128 v[120:123], v192 offset:512
	s_waitcnt lgkmcnt(0)
	v_pk_mul_f32 v[100:101], v[118:119], v[122:123]
	v_pk_mul_f32 v[124:125], v[116:117], v[120:121]
	ds_read_b128 v[120:123], v192 offset:528
	s_waitcnt lgkmcnt(0)
	v_pk_mul_f32 v[168:169], v[110:111], v[122:123]
	v_pk_mul_f32 v[122:123], v[108:109], v[120:121]
	v_cvt_pk_bf16_f32 v120, v124, v125
	v_cvt_pk_bf16_f32 v121, v100, v101
	v_cvt_pk_bf16_f32 v122, v122, v123
	v_cvt_pk_bf16_f32 v123, v168, v169
	ds_bpermute_b32 v120, v206, v120
	ds_bpermute_b32 v121, v206, v121
	ds_bpermute_b32 v122, v206, v122
	ds_bpermute_b32 v123, v206, v123
	s_waitcnt lgkmcnt(0)
	global_store_dwordx4 v[92:93], v[120:123], off offset:256
	s_waitcnt lgkmcnt(0)
	global_store_dwordx4 v126, v[216:219], s[20:21] offset:512
	global_store_dwordx4 v126, v[220:223], s[100:101] offset:512
	v_mul_f32_e32 v92, v117, v117
	v_mul_f32_e32 v93, v119, v119
	v_fmac_f32_e32 v92, v116, v116
	v_fmac_f32_e32 v93, v118, v118
	v_add_f32_e32 v92, v92, v93
	v_mul_f32_e32 v93, v109, v109
	v_mul_f32_e32 v100, v111, v111
	v_fmac_f32_e32 v93, v108, v108
	v_fmac_f32_e32 v100, v110, v110
	v_add_f32_e32 v93, v93, v100
	v_and_b32_e32 v100, 64, v242
	v_add_f32_e32 v92, v92, v93
	v_xor_b32_e32 v93, 16, v242
	v_add_u32_e32 v100, 64, v100
	v_cmp_lt_i32_e32 vcc, v93, v100
	v_add_f32_e32 v92, v172, v92
	s_nop 0
	v_cndmask_b32_e32 v93, v242, v93, vcc
	v_lshlrev_b32_e32 v93, 2, v93
	ds_bpermute_b32 v93, v93, v92
	s_waitcnt lgkmcnt(0)
	v_add_f32_e32 v92, v92, v93
	v_xor_b32_e32 v93, 32, v242
	v_cmp_lt_i32_e32 vcc, v93, v100
	s_nop 1
	v_cndmask_b32_e32 v93, v242, v93, vcc
	v_lshlrev_b32_e32 v93, 2, v93
	ds_bpermute_b32 v93, v93, v92
	s_and_saveexec_b64 s[54:55], s[44:45]
	s_cbranch_execz .LBB0_225
	v_lshlrev_b64 v[100:101], 6, v[234:235]
	v_lshl_add_u64 v[100:101], s[22:23], 0, v[100:101]
	v_lshl_add_u64 v[100:101], s[76:77], 2, v[100:101]
	s_lshl_b32 s92, s6, 2
	v_lshl_add_u64 v[100:101], v[100:101], 0, s[92:93]
	s_waitcnt lgkmcnt(0)
	v_add_f32_e32 v92, v92, v93
	global_store_dword v[100:101], v92, off

; #define LAS __attribute__((address_space(3)))
; __device__ __forceinline__ unsigned cvt_pk_bf16(float lo, float hi) { const cvt_f32x2_t v = {lo, hi}; const cvt_bf16x2_t b = __builtin_convertvector(v, cvt_bf16x2_t); return __builtin_bit_cast(unsigned, b); }
; __device__ __forceinline__ float sq4(f32x4 v) { return (v[0] * v[0] + v[1] * v[1]) + (v[2] * v[2] + v[3] * v[3]); }
;     __device__ __forceinline__ void operator()(const f32x4 (&acc)[2][2][4][2], const Unit& u, int wr, int wc, int fr, int fq) const {
;     ...
;             for (int m = 0; m < 4; ++m) {
;                 const int row = u.pm * 256 + ai * 128 + wr * 64 + m * 16 + fr;
;                 const size_t off = (size_t)row * DM + col0;
;                 float ss = 0.f;
; #pragma unroll
;                 for (int bj = 0; bj < 2; ++bj) {
;                     const f32x4 xo0 = xr[m][bj][0] + *(const LAS f32x4*)(gtp + 128 * bj) * acc[ai][bj][m][0], xo1 = xr[m][bj][1] + *(const LAS f32x4*)(gtp + 128 * bj + 4) * acc[ai][bj][m][1];
;                     *(f32x4*)(xout + off + 128 * bj) = xo0; *(f32x4*)(xout + off + 128 * bj + 4) = xo1;
;                     if (gmn) { ss += sq4(xo0) + sq4(xo1); const f32x4 a = xo0 * *(const LAS f32x4*)(gmp + 128 * bj), c = xo1 * *(const LAS f32x4*)(gmp + 128 * bj + 4);
;                         u32x4 w; w.x = cvt_pk_bf16(a[0], a[1]); w.y = cvt_pk_bf16(a[2], a[3]); w.z = cvt_pk_bf16(c[0], c[1]); w.w = cvt_pk_bf16(c[2], c[3]); *(u32x4*)(AX + off + 128 * bj) = w; }
;                 }
;                 if (gmn) { ss += __shfl_xor(ss, 16); ss += __shfl_xor(ss, 32); if (fq == 0) statx[(size_t)row * 16 + u.pn * 4 + wc] = ss; }
.LBB0_228:
	s_waitcnt lgkmcnt(0)
	v_lshlrev_b64 v[92:93], 10, v[232:233]
	v_lshl_add_u64 v[94:95], v[92:93], 0, v[224:225]
	v_pk_fma_f32 v[98:99], v[98:99], v[150:151], v[166:167]
	v_pk_fma_f32 v[96:97], v[96:97], v[148:149], v[164:165]
	v_pk_fma_f32 v[102:103], v[90:91], v[142:143], v[162:163]
	v_pk_fma_f32 v[100:101], v[88:89], v[140:141], v[160:161]
	v_lshl_add_u64 v[108:109], v[94:95], 2, s[20:21]
	v_lshl_add_u32 v108, v94, 2, v246
	s_mov_b64 s[54:55], -1
	s_and_b64 vcc, exec, s[46:47]
	v_pk_fma_f32 v[92:93], v[84:85], v[132:133], v[156:157]
	v_pk_fma_f32 v[88:89], v[76:77], v[128:129], v[152:153]
	ds_write_b128 v208, v[96:99]
	ds_write_b128 v208, v[100:103] offset:16
	ds_read_b128 v[216:219], v210
	ds_read_b128 v[220:223], v210 offset:1152
	s_cbranch_vccnz .Lxn_ph_5488
	v_mul_f32_e32 v76, v97, v97
	v_mul_f32_e32 v77, v99, v99
	ds_read_b128 v[116:119], v192
	ds_read_b128 v[120:123], v192 offset:16
	v_fmac_f32_e32 v76, v96, v96
	v_fmac_f32_e32 v77, v98, v98
	v_add_f32_e32 v76, v76, v77
	v_mul_f32_e32 v77, v101, v101
	v_mul_f32_e32 v84, v103, v103
	v_fmac_f32_e32 v77, v100, v100
	v_fmac_f32_e32 v84, v102, v102
	v_add_f32_e32 v77, v77, v84
	v_add_f32_e32 v110, v76, v77
	s_waitcnt lgkmcnt(1)
	v_pk_mul_f32 v[76:77], v[98:99], v[118:119]
	v_pk_mul_f32 v[84:85], v[96:97], v[116:117]
	s_waitcnt lgkmcnt(0)
	v_pk_mul_f32 v[90:91], v[102:103], v[122:123]
	v_pk_mul_f32 v[98:99], v[100:101], v[120:121]
	v_cvt_pk_bf16_f32 v96, v84, v85
	v_cvt_pk_bf16_f32 v97, v76, v77
	v_cvt_pk_bf16_f32 v98, v98, v99
	v_cvt_pk_bf16_f32 v99, v90, v91
	v_lshl_add_u64 v[76:77], v[94:95], 1, s[16:17]
	v_lshl_add_u64 v[76:77], v[204:205], 0, v[76:77]
	v_pk_fma_f32 v[94:95], v[86:87], v[134:135], v[158:159]
	ds_bpermute_b32 v96, v206, v96
	ds_bpermute_b32 v97, v206, v97
	ds_bpermute_b32 v98, v206, v98
	ds_bpermute_b32 v99, v206, v99
	s_waitcnt lgkmcnt(0)
	global_store_dwordx4 v[76:77], v[96:99], off
	s_waitcnt lgkmcnt(0)
	global_store_dwordx4 v108, v[216:219], s[20:21]
	global_store_dwordx4 v108, v[220:223], s[100:101]
	v_pk_fma_f32 v[90:91], v[78:79], v[130:131], v[154:155]
	ds_write_b128 v208, v[92:95]
	ds_write_b128 v208, v[88:91] offset:16
	ds_read_b128 v[216:219], v210
	ds_read_b128 v[220:223], v210 offset:1152
	ds_read_b128 v[96:99], v192 offset:512
	s_waitcnt lgkmcnt(0)
	v_pk_mul_f32 v[84:85], v[94:95], v[98:99]
	v_pk_mul_f32 v[100:101], v[92:93], v[96:97]
	ds_read_b128 v[96:99], v192 offset:528
	s_waitcnt lgkmcnt(0)
	v_pk_mul_f32 v[102:103], v[90:91], v[98:99]
	v_pk_mul_f32 v[98:99], v[88:89], v[96:97]
	v_cvt_pk_bf16_f32 v96, v100, v101
	v_cvt_pk_bf16_f32 v97, v84, v85
	v_cvt_pk_bf16_f32 v98, v98, v99
	v_cvt_pk_bf16_f32 v99, v102, v103
	ds_bpermute_b32 v96, v206, v96
	ds_bpermute_b32 v97, v206, v97
	ds_bpermute_b32 v98, v206, v98
	ds_bpermute_b32 v99, v206, v99
	s_waitcnt lgkmcnt(0)
	global_store_dwordx4 v[76:77], v[96:99], off offset:256
	s_waitcnt lgkmcnt(0)
	global_store_dwordx4 v108, v[216:219], s[20:21] offset:512
	global_store_dwordx4 v108, v[220:223], s[100:101] offset:512
	v_mul_f32_e32 v76, v93, v93
	v_mul_f32_e32 v77, v95, v95
	v_fmac_f32_e32 v76, v92, v92
	v_fmac_f32_e32 v77, v94, v94
	v_add_f32_e32 v76, v76, v77
	v_mul_f32_e32 v77, v89, v89
	v_mul_f32_e32 v84, v91, v91
	v_fmac_f32_e32 v77, v88, v88
	v_fmac_f32_e32 v84, v90, v90
	v_add_f32_e32 v77, v77, v84
	v_and_b32_e32 v84, 64, v242
	v_add_f32_e32 v76, v76, v77
	v_xor_b32_e32 v77, 16, v242
	v_add_u32_e32 v84, 64, v84
	v_cmp_lt_i32_e32 vcc, v77, v84
	v_add_f32_e32 v76, v110, v76
	s_nop 0
	v_cndmask_b32_e32 v77, v242, v77, vcc
	v_lshlrev_b32_e32 v77, 2, v77
	ds_bpermute_b32 v77, v77, v76
	s_waitcnt lgkmcnt(0)
	v_add_f32_e32 v76, v76, v77
	v_xor_b32_e32 v77, 32, v242
	v_cmp_lt_i32_e32 vcc, v77, v84
	s_nop 1
	v_cndmask_b32_e32 v77, v242, v77, vcc
	v_lshlrev_b32_e32 v77, 2, v77
	ds_bpermute_b32 v77, v77, v76
	s_and_saveexec_b64 s[54:55], s[44:45]
	s_cbranch_execz .LBB0_231
	v_lshlrev_b64 v[84:85], 6, v[232:233]
	v_lshl_add_u64 v[84:85], s[22:23], 0, v[84:85]
	v_lshl_add_u64 v[84:85], s[76:77], 2, v[84:85]
	s_lshl_b32 s92, s6, 2
	v_lshl_add_u64 v[84:85], v[84:85], 0, s[92:93]
	s_waitcnt lgkmcnt(0)
	v_add_f32_e32 v76, v76, v77
	global_store_dword v[84:85], v76, off

; #define LAS __attribute__((address_space(3)))
; __device__ __forceinline__ unsigned cvt_pk_bf16(float lo, float hi) { const cvt_f32x2_t v = {lo, hi}; const cvt_bf16x2_t b = __builtin_convertvector(v, cvt_bf16x2_t); return __builtin_bit_cast(unsigned, b); }
; __device__ __forceinline__ float sq4(f32x4 v) { return (v[0] * v[0] + v[1] * v[1]) + (v[2] * v[2] + v[3] * v[3]); }
;     __device__ __forceinline__ void operator()(const f32x4 (&acc)[2][2][4][2], const Unit& u, int wr, int wc, int fr, int fq) const {
;     ...
;             for (int m = 0; m < 4; ++m) {
;                 const int row = u.pm * 256 + ai * 128 + wr * 64 + m * 16 + fr;
;                 const size_t off = (size_t)row * DM + col0;
;                 float ss = 0.f;
; #pragma unroll
;                 for (int bj = 0; bj < 2; ++bj) {
;                     const f32x4 xo0 = xr[m][bj][0] + *(const LAS f32x4*)(gtp + 128 * bj) * acc[ai][bj][m][0], xo1 = xr[m][bj][1] + *(const LAS f32x4*)(gtp + 128 * bj + 4) * acc[ai][bj][m][1];
;                     *(f32x4*)(xout + off + 128 * bj) = xo0; *(f32x4*)(xout + off + 128 * bj + 4) = xo1;
;                     if (gmn) { ss += sq4(xo0) + sq4(xo1); const f32x4 a = xo0 * *(const LAS f32x4*)(gmp + 128 * bj), c = xo1 * *(const LAS f32x4*)(gmp + 128 * bj + 4);
;                         u32x4 w; w.x = cvt_pk_bf16(a[0], a[1]); w.y = cvt_pk_bf16(a[2], a[3]); w.z = cvt_pk_bf16(c[0], c[1]); w.w = cvt_pk_bf16(c[2], c[3]); *(u32x4*)(AX + off + 128 * bj) = w; }
;                 }
;                 if (gmn) { ss += __shfl_xor(ss, 16); ss += __shfl_xor(ss, 32); if (fq == 0) statx[(size_t)row * 16 + u.pn * 4 + wc] = ss; }
.LBB0_234:
	s_waitcnt lgkmcnt(0)
	v_lshlrev_b64 v[76:77], 10, v[230:231]
	v_lshl_add_u64 v[78:79], v[76:77], 0, v[224:225]
	v_pk_fma_f32 v[82:83], v[82:83], v[150:151], v[146:147]
	v_pk_fma_f32 v[80:81], v[80:81], v[148:149], v[144:145]
	v_pk_fma_f32 v[86:87], v[74:75], v[142:143], v[138:139]
	v_pk_fma_f32 v[84:85], v[72:73], v[140:141], v[136:137]
	v_lshl_add_u64 v[88:89], v[78:79], 2, s[20:21]
	v_lshl_add_u32 v88, v78, 2, v246
	s_mov_b64 s[54:55], -1
	s_and_b64 vcc, exec, s[46:47]
	v_pk_fma_f32 v[76:77], v[68:69], v[132:133], v[112:113]
	v_pk_fma_f32 v[72:73], v[64:65], v[128:129], v[104:105]
	ds_write_b128 v208, v[80:83]
	ds_write_b128 v208, v[84:87] offset:16
	ds_read_b128 v[216:219], v210
	ds_read_b128 v[220:223], v210 offset:1152
	s_cbranch_vccnz .Lxn_ph_5597
	v_mul_f32_e32 v64, v81, v81
	v_mul_f32_e32 v65, v83, v83
	ds_read_b128 v[90:93], v192
	ds_read_b128 v[94:97], v192 offset:16
	v_fmac_f32_e32 v64, v80, v80
	v_fmac_f32_e32 v65, v82, v82
	v_add_f32_e32 v64, v64, v65
	v_mul_f32_e32 v65, v85, v85
	v_mul_f32_e32 v68, v87, v87
	v_fmac_f32_e32 v65, v84, v84
	v_fmac_f32_e32 v68, v86, v86
	v_add_f32_e32 v65, v65, v68
	v_add_f32_e32 v98, v64, v65
	s_waitcnt lgkmcnt(1)
	v_pk_mul_f32 v[64:65], v[82:83], v[92:93]
	v_pk_mul_f32 v[68:69], v[80:81], v[90:91]
	s_waitcnt lgkmcnt(0)
	v_pk_mul_f32 v[74:75], v[86:87], v[96:97]
	v_pk_mul_f32 v[82:83], v[84:85], v[94:95]
	v_cvt_pk_bf16_f32 v80, v68, v69
	v_cvt_pk_bf16_f32 v81, v64, v65
	v_cvt_pk_bf16_f32 v82, v82, v83
	v_cvt_pk_bf16_f32 v83, v74, v75
	v_lshl_add_u64 v[64:65], v[78:79], 1, s[16:17]
	v_lshl_add_u64 v[64:65], v[204:205], 0, v[64:65]
	v_pk_fma_f32 v[78:79], v[70:71], v[134:135], v[114:115]
	ds_bpermute_b32 v80, v206, v80
	ds_bpermute_b32 v81, v206, v81
	ds_bpermute_b32 v82, v206, v82
	ds_bpermute_b32 v83, v206, v83
	s_waitcnt lgkmcnt(0)
	global_store_dwordx4 v[64:65], v[80:83], off
	s_waitcnt lgkmcnt(0)
	global_store_dwordx4 v88, v[216:219], s[20:21]
	global_store_dwordx4 v88, v[220:223], s[100:101]
	v_pk_fma_f32 v[74:75], v[66:67], v[130:131], v[106:107]
	ds_write_b128 v208, v[76:79]
	ds_write_b128 v208, v[72:75] offset:16
	ds_read_b128 v[216:219], v210
	ds_read_b128 v[220:223], v210 offset:1152
	ds_read_b128 v[80:83], v192 offset:512
	s_waitcnt lgkmcnt(0)
	v_pk_mul_f32 v[68:69], v[78:79], v[82:83]
	v_pk_mul_f32 v[84:85], v[76:77], v[80:81]
	ds_read_b128 v[80:83], v192 offset:528
	s_waitcnt lgkmcnt(0)
	v_pk_mul_f32 v[86:87], v[74:75], v[82:83]
	v_pk_mul_f32 v[82:83], v[72:73], v[80:81]
	v_cvt_pk_bf16_f32 v80, v84, v85
	v_cvt_pk_bf16_f32 v81, v68, v69
	v_cvt_pk_bf16_f32 v82, v82, v83
	v_cvt_pk_bf16_f32 v83, v86, v87
	ds_bpermute_b32 v80, v206, v80
	ds_bpermute_b32 v81, v206, v81
	ds_bpermute_b32 v82, v206, v82
	ds_bpermute_b32 v83, v206, v83
	s_waitcnt lgkmcnt(0)
	global_store_dwordx4 v[64:65], v[80:83], off offset:256
	s_waitcnt lgkmcnt(0)
	global_store_dwordx4 v88, v[216:219], s[20:21] offset:512
	global_store_dwordx4 v88, v[220:223], s[100:101] offset:512
	v_mul_f32_e32 v64, v77, v77
	v_mul_f32_e32 v65, v79, v79
	v_fmac_f32_e32 v64, v76, v76
	v_fmac_f32_e32 v65, v78, v78
	v_add_f32_e32 v64, v64, v65
	v_mul_f32_e32 v65, v73, v73
	v_mul_f32_e32 v68, v75, v75
	v_fmac_f32_e32 v65, v72, v72
	v_fmac_f32_e32 v68, v74, v74
	v_add_f32_e32 v65, v65, v68
	v_and_b32_e32 v68, 64, v242
	v_add_f32_e32 v64, v64, v65
	v_xor_b32_e32 v65, 16, v242
	v_add_u32_e32 v68, 64, v68
	v_cmp_lt_i32_e32 vcc, v65, v68
	v_add_f32_e32 v64, v98, v64
	s_nop 0
	v_cndmask_b32_e32 v65, v242, v65, vcc
	v_lshlrev_b32_e32 v65, 2, v65
	ds_bpermute_b32 v65, v65, v64
	s_waitcnt lgkmcnt(0)
	v_add_f32_e32 v64, v64, v65
	v_xor_b32_e32 v65, 32, v242
	v_cmp_lt_i32_e32 vcc, v65, v68
	s_nop 1
	v_cndmask_b32_e32 v65, v242, v65, vcc
	v_lshlrev_b32_e32 v65, 2, v65
	ds_bpermute_b32 v65, v65, v64
	s_and_saveexec_b64 s[54:55], s[44:45]
	s_cbranch_execz .LBB0_237
	v_lshlrev_b64 v[68:69], 6, v[230:231]
	v_lshl_add_u64 v[68:69], s[22:23], 0, v[68:69]
	v_lshl_add_u64 v[68:69], s[76:77], 2, v[68:69]
	s_lshl_b32 s92, s6, 2
	v_lshl_add_u64 v[68:69], v[68:69], 0, s[92:93]
	s_waitcnt lgkmcnt(0)
	v_add_f32_e32 v64, v64, v65
	global_store_dword v[68:69], v64, off

; #define LAS __attribute__((address_space(3)))
; __device__ __forceinline__ unsigned cvt_pk_bf16(float lo, float hi) { const cvt_f32x2_t v = {lo, hi}; const cvt_bf16x2_t b = __builtin_convertvector(v, cvt_bf16x2_t); return __builtin_bit_cast(unsigned, b); }
; __device__ __forceinline__ float sq4(f32x4 v) { return (v[0] * v[0] + v[1] * v[1]) + (v[2] * v[2] + v[3] * v[3]); }
;     __device__ __forceinline__ void operator()(const f32x4 (&acc)[2][2][4][2], const Unit& u, int wr, int wc, int fr, int fq) const {
;     ...
;             for (int m = 0; m < 4; ++m) { const size_t off = (size_t)(u.pm * 256 + ai * 128 + wr * 64 + m * 16 + fr) * DM + col0;
; #pragma unroll
;                 for (int bj = 0; bj < 2; ++bj)
; #pragma unroll
;                     for (int n = 0; n < 2; ++n) xr[m][bj][n] = *(const f32x4*)(xin + off + 128 * bj + 4 * n); }
;             asm volatile("" ::: "memory");
; #pragma unroll
;             for (int m = 0; m < 4; ++m) {
;                 const int row = u.pm * 256 + ai * 128 + wr * 64 + m * 16 + fr;
;                 const size_t off = (size_t)row * DM + col0;
;                 float ss = 0.f;
; #pragma unroll
;                 for (int bj = 0; bj < 2; ++bj) {
;                     const f32x4 xo0 = xr[m][bj][0] + *(const LAS f32x4*)(gtp + 128 * bj) * acc[ai][bj][m][0], xo1 = xr[m][bj][1] + *(const LAS f32x4*)(gtp + 128 * bj + 4) * acc[ai][bj][m][1];
;                     *(f32x4*)(xout + off + 128 * bj) = xo0; *(f32x4*)(xout + off + 128 * bj + 4) = xo1;
;                     if (gmn) { ss += sq4(xo0) + sq4(xo1); const f32x4 a = xo0 * *(const LAS f32x4*)(gmp + 128 * bj), c = xo1 * *(const LAS f32x4*)(gmp + 128 * bj + 4);
;                         u32x4 w; w.x = cvt_pk_bf16(a[0], a[1]); w.y = cvt_pk_bf16(a[2], a[3]); w.z = cvt_pk_bf16(c[0], c[1]); w.w = cvt_pk_bf16(c[2], c[3]); *(u32x4*)(AX + off + 128 * bj) = w; }
;                 }
;                 if (gmn) { ss += __shfl_xor(ss, 16); ss += __shfl_xor(ss, 32); if (fq == 0) statx[(size_t)row * 16 + u.pn * 4 + wc] = ss; }
.LBB0_240:
	v_add_u32_e32 v134, 0x80, v226
	v_ashrrev_i32_e32 v135, 31, v134
	s_waitcnt lgkmcnt(0)
	v_lshlrev_b64 v[64:65], 12, v[134:135]
	v_add_u32_e32 v132, 0x90, v226
	v_lshl_add_u64 v[64:65], v[228:229], 0, v[64:65]
	v_ashrrev_i32_e32 v133, 31, v132
	global_load_dwordx4 v[136:139], v[64:65], off offset:16
	global_load_dwordx4 v[140:143], v[64:65], off
	global_load_dwordx4 v[120:123], v[64:65], off offset:528
	global_load_dwordx4 v[124:127], v[64:65], off offset:512
	v_lshlrev_b64 v[64:65], 12, v[132:133]
	v_add_u32_e32 v130, 0xa0, v226
	v_lshl_add_u64 v[64:65], v[228:229], 0, v[64:65]
	v_ashrrev_i32_e32 v131, 31, v130
	global_load_dwordx4 v[112:115], v[64:65], off offset:16
	global_load_dwordx4 v[116:119], v[64:65], off
	global_load_dwordx4 v[104:107], v[64:65], off offset:528
	global_load_dwordx4 v[108:111], v[64:65], off offset:512
	v_lshlrev_b64 v[64:65], 12, v[130:131]
	v_add_u32_e32 v128, 0xb0, v226
	v_lshl_add_u64 v[64:65], v[228:229], 0, v[64:65]
	v_ashrrev_i32_e32 v129, 31, v128
	global_load_dwordx4 v[96:99], v[64:65], off offset:16
	global_load_dwordx4 v[100:103], v[64:65], off
	global_load_dwordx4 v[88:91], v[64:65], off offset:528
	global_load_dwordx4 v[92:95], v[64:65], off offset:512
	v_lshlrev_b64 v[64:65], 12, v[128:129]
	v_lshl_add_u64 v[68:69], v[228:229], 0, v[64:65]
	global_load_dwordx4 v[72:75], v[68:69], off offset:16
	global_load_dwordx4 v[80:83], v[68:69], off
	global_load_dwordx4 v[64:67], v[68:69], off offset:528
	s_nop 0
	global_load_dwordx4 v[68:71], v[68:69], off offset:512
	v_lshlrev_b64 v[76:77], 10, v[134:135]
	v_lshl_add_u64 v[144:145], v[76:77], 0, v[224:225]
	ds_read_b128 v[84:87], v249
	ds_read_b128 v[76:79], v249 offset:16
	s_and_b64 vcc, exec, s[46:47]
	s_waitcnt vmcnt(15) lgkmcnt(0)
	v_pk_fma_f32 v[58:59], v[58:59], v[78:79], v[138:139]
	s_waitcnt vmcnt(14)
	v_pk_fma_f32 v[62:63], v[62:63], v[86:87], v[142:143]
	v_pk_fma_f32 v[60:61], v[60:61], v[84:85], v[140:141]
	v_pk_fma_f32 v[56:57], v[56:57], v[76:77], v[136:137]
	v_lshl_add_u64 v[136:137], v[144:145], 2, s[20:21]
	v_lshl_add_u32 v136, v144, 2, v246
	v_mov_b32_e32 v140, 0
	v_lshl_add_u64 v[138:139], v[144:145], 1, s[16:17]
	v_lshl_add_u64 v[138:139], v[204:205], 0, v[138:139]
	ds_write_b128 v208, v[60:63]
	ds_write_b128 v208, v[56:59] offset:16
	ds_read_b128 v[216:219], v210
	ds_read_b128 v[220:223], v210 offset:1152
	s_cbranch_vccnz .Lxn_ph_5744
	v_mov_b32_e32 v142, v61
	v_mov_b32_e32 v143, v57
	v_mov_b32_e32 v140, v60
	v_mov_b32_e32 v141, v56
	v_pk_mul_f32 v[142:143], v[142:143], v[142:143]
	v_mov_b32_e32 v144, v63
	v_mov_b32_e32 v145, v59
	v_pk_fma_f32 v[140:141], v[140:141], v[140:141], v[142:143]
	v_mov_b32_e32 v142, v62
	v_mov_b32_e32 v143, v58
	v_pk_mul_f32 v[144:145], v[144:145], v[144:145]
	s_nop 0
	v_pk_fma_f32 v[142:143], v[142:143], v[142:143], v[144:145]
	s_nop 0
	v_pk_add_f32 v[140:141], v[140:141], v[142:143]
	ds_read_b128 v[142:145], v192
	ds_read_b128 v[146:149], v192 offset:16
	v_add_f32_e32 v140, v140, v141
	s_waitcnt lgkmcnt(1)
	v_pk_mul_f32 v[62:63], v[62:63], v[144:145]
	v_pk_mul_f32 v[60:61], v[60:61], v[142:143]
	s_waitcnt lgkmcnt(0)
	v_pk_mul_f32 v[142:143], v[58:59], v[148:149]
	v_pk_mul_f32 v[58:59], v[56:57], v[146:147]
	v_cvt_pk_bf16_f32 v56, v60, v61
	v_cvt_pk_bf16_f32 v57, v62, v63
	v_cvt_pk_bf16_f32 v58, v58, v59
	v_cvt_pk_bf16_f32 v59, v142, v143
	ds_bpermute_b32 v56, v206, v56
	ds_bpermute_b32 v57, v206, v57
	ds_bpermute_b32 v58, v206, v58
	ds_bpermute_b32 v59, v206, v59
	s_waitcnt lgkmcnt(0)
	global_store_dwordx4 v[138:139], v[56:59], off
	s_waitcnt lgkmcnt(0)
	global_store_dwordx4 v136, v[216:219], s[20:21]
	global_store_dwordx4 v136, v[220:223], s[100:101]
.LBB0_242:
	ds_read_b128 v[60:63], v249 offset:512
	ds_read_b128 v[56:59], v249 offset:528
	s_and_b64 vcc, exec, s[46:47]
	s_waitcnt vmcnt(14) lgkmcnt(1)
	v_pk_fma_f32 v[54:55], v[54:55], v[62:63], v[126:127]
	v_pk_fma_f32 v[52:53], v[52:53], v[60:61], v[124:125]
	s_waitcnt lgkmcnt(0)
	v_pk_fma_f32 v[50:51], v[50:51], v[58:59], v[122:123]
	v_pk_fma_f32 v[48:49], v[48:49], v[56:57], v[120:121]
	ds_write_b128 v208, v[52:55]
	ds_write_b128 v208, v[48:51] offset:16
	ds_read_b128 v[216:219], v210
	ds_read_b128 v[220:223], v210 offset:1152
	s_cbranch_vccnz .Lxn_ph_5787
	ds_read_b128 v[120:123], v192 offset:512
	ds_read_b128 v[124:127], v192 offset:528
	s_waitcnt lgkmcnt(1)
	v_pk_mul_f32 v[120:121], v[52:53], v[120:121]
	s_waitcnt lgkmcnt(0)
	v_pk_mul_f32 v[124:125], v[48:49], v[124:125]
	v_mul_f32_e32 v49, v49, v49
	v_mul_f32_e32 v53, v53, v53
	v_fmac_f32_e32 v49, v48, v48
	v_mul_f32_e32 v48, v51, v51
	v_pk_mul_f32 v[126:127], v[50:51], v[126:127]
	v_fmac_f32_e32 v53, v52, v52
	v_mul_f32_e32 v52, v55, v55
	v_fmac_f32_e32 v48, v50, v50
	v_and_b32_e32 v50, 64, v242
	v_fmac_f32_e32 v52, v54, v54
	v_add_f32_e32 v48, v49, v48
	v_xor_b32_e32 v49, 16, v242
	v_add_u32_e32 v50, 64, v50
	v_add_f32_e32 v52, v53, v52
	v_cmp_lt_i32_e32 vcc, v49, v50
	v_add_f32_e32 v48, v52, v48
	v_add_f32_e32 v48, v140, v48
	v_cndmask_b32_e32 v49, v242, v49, vcc
	v_lshlrev_b32_e32 v49, 2, v49
	ds_bpermute_b32 v49, v49, v48
	v_pk_mul_f32 v[122:123], v[54:55], v[122:123]
	v_cvt_pk_bf16_f32 v120, v120, v121
	v_cvt_pk_bf16_f32 v121, v122, v123
	v_cvt_pk_bf16_f32 v122, v124, v125
	s_waitcnt lgkmcnt(0)
	v_add_f32_e32 v48, v48, v49
	v_xor_b32_e32 v49, 32, v242
	v_cmp_lt_i32_e32 vcc, v49, v50
	v_cvt_pk_bf16_f32 v123, v126, v127
	ds_bpermute_b32 v120, v206, v120
	ds_bpermute_b32 v121, v206, v121
	ds_bpermute_b32 v122, v206, v122
	ds_bpermute_b32 v123, v206, v123
	s_waitcnt lgkmcnt(0)
	global_store_dwordx4 v[138:139], v[120:123], off offset:256
	s_waitcnt lgkmcnt(0)
	global_store_dwordx4 v136, v[216:219], s[20:21] offset:512
	global_store_dwordx4 v136, v[220:223], s[100:101] offset:512
	v_cndmask_b32_e32 v49, v242, v49, vcc
	v_lshlrev_b32_e32 v49, 2, v49
	ds_bpermute_b32 v49, v49, v48
	s_and_saveexec_b64 s[54:55], s[44:45]
	s_cbranch_execz .LBB0_245
	v_lshlrev_b64 v[50:51], 6, v[134:135]
	v_lshl_add_u64 v[50:51], s[22:23], 0, v[50:51]
	v_lshl_add_u64 v[50:51], s[76:77], 2, v[50:51]
	s_lshl_b32 s92, s6, 2
	v_lshl_add_u64 v[50:51], v[50:51], 0, s[92:93]
	s_waitcnt lgkmcnt(0)
	v_add_f32_e32 v48, v48, v49
	global_store_dword v[50:51], v48, off

; #define LAS __attribute__((address_space(3)))
; __device__ __forceinline__ unsigned cvt_pk_bf16(float lo, float hi) { const cvt_f32x2_t v = {lo, hi}; const cvt_bf16x2_t b = __builtin_convertvector(v, cvt_bf16x2_t); return __builtin_bit_cast(unsigned, b); }
; __device__ __forceinline__ float sq4(f32x4 v) { return (v[0] * v[0] + v[1] * v[1]) + (v[2] * v[2] + v[3] * v[3]); }
;     __device__ __forceinline__ void operator()(const f32x4 (&acc)[2][2][4][2], const Unit& u, int wr, int wc, int fr, int fq) const {
;     ...
;             for (int m = 0; m < 4; ++m) {
;                 const int row = u.pm * 256 + ai * 128 + wr * 64 + m * 16 + fr;
;                 const size_t off = (size_t)row * DM + col0;
;                 float ss = 0.f;
; #pragma unroll
;                 for (int bj = 0; bj < 2; ++bj) {
;                     const f32x4 xo0 = xr[m][bj][0] + *(const LAS f32x4*)(gtp + 128 * bj) * acc[ai][bj][m][0], xo1 = xr[m][bj][1] + *(const LAS f32x4*)(gtp + 128 * bj + 4) * acc[ai][bj][m][1];
;                     *(f32x4*)(xout + off + 128 * bj) = xo0; *(f32x4*)(xout + off + 128 * bj + 4) = xo1;
;                     if (gmn) { ss += sq4(xo0) + sq4(xo1); const f32x4 a = xo0 * *(const LAS f32x4*)(gmp + 128 * bj), c = xo1 * *(const LAS f32x4*)(gmp + 128 * bj + 4);
;                         u32x4 w; w.x = cvt_pk_bf16(a[0], a[1]); w.y = cvt_pk_bf16(a[2], a[3]); w.z = cvt_pk_bf16(c[0], c[1]); w.w = cvt_pk_bf16(c[2], c[3]); *(u32x4*)(AX + off + 128 * bj) = w; }
;                 }
;                 if (gmn) { ss += __shfl_xor(ss, 16); ss += __shfl_xor(ss, 32); if (fq == 0) statx[(size_t)row * 16 + u.pn * 4 + wc] = ss; }
.LBB0_246:
	s_waitcnt lgkmcnt(0)
	v_lshlrev_b64 v[48:49], 10, v[132:133]
	v_lshl_add_u64 v[120:121], v[48:49], 0, v[224:225]
	s_waitcnt vmcnt(14)
	v_pk_fma_f32 v[48:49], v[46:47], v[86:87], v[118:119]
	v_pk_fma_f32 v[46:47], v[44:45], v[84:85], v[116:117]
	v_pk_fma_f32 v[52:53], v[42:43], v[78:79], v[114:115]
	v_pk_fma_f32 v[50:51], v[40:41], v[76:77], v[112:113]
	v_lshl_add_u64 v[54:55], v[120:121], 2, s[20:21]
	v_lshl_add_u32 v54, v120, 2, v246
	s_mov_b64 s[54:55], -1
	s_and_b64 vcc, exec, s[46:47]
	s_waitcnt vmcnt(12)
	v_pk_fma_f32 v[44:45], v[36:37], v[60:61], v[108:109]
	v_pk_fma_f32 v[40:41], v[28:29], v[56:57], v[104:105]
	ds_write_b128 v208, v[46:49]
	ds_write_b128 v208, v[50:53] offset:16
	ds_read_b128 v[216:219], v210
	ds_read_b128 v[220:223], v210 offset:1152
	s_cbranch_vccnz .Lxn_ph_5858
	v_mul_f32_e32 v28, v47, v47
	v_mul_f32_e32 v29, v49, v49
	ds_read_b128 v[112:115], v192
	ds_read_b128 v[116:119], v192 offset:16
	v_fmac_f32_e32 v28, v46, v46
	v_fmac_f32_e32 v29, v48, v48
	v_add_f32_e32 v28, v28, v29
	v_mul_f32_e32 v29, v51, v51
	v_mul_f32_e32 v36, v53, v53
	v_fmac_f32_e32 v29, v50, v50
	v_fmac_f32_e32 v36, v52, v52
	v_add_f32_e32 v29, v29, v36
	v_add_f32_e32 v108, v28, v29
	s_waitcnt lgkmcnt(1)
	v_pk_mul_f32 v[28:29], v[48:49], v[114:115]
	v_pk_mul_f32 v[36:37], v[46:47], v[112:113]
	s_waitcnt lgkmcnt(0)
	v_pk_mul_f32 v[42:43], v[52:53], v[118:119]
	v_pk_mul_f32 v[48:49], v[50:51], v[116:117]
	v_cvt_pk_bf16_f32 v46, v36, v37
	v_cvt_pk_bf16_f32 v47, v28, v29
	v_cvt_pk_bf16_f32 v48, v48, v49
	v_cvt_pk_bf16_f32 v49, v42, v43
	v_lshl_add_u64 v[28:29], v[120:121], 1, s[16:17]
	ds_bpermute_b32 v46, v206, v46
	ds_bpermute_b32 v47, v206, v47
	ds_bpermute_b32 v48, v206, v48
	ds_bpermute_b32 v49, v206, v49
	s_waitcnt lgkmcnt(0)
	v_lshl_add_u64 v[28:29], v[204:205], 0, v[28:29]
	global_store_dwordx4 v[28:29], v[46:49], off
	s_waitcnt lgkmcnt(0)
	global_store_dwordx4 v54, v[216:219], s[20:21]
	global_store_dwordx4 v54, v[220:223], s[100:101]
	v_pk_fma_f32 v[42:43], v[30:31], v[58:59], v[106:107]
	s_nop 0
	v_pk_fma_f32 v[46:47], v[38:39], v[62:63], v[110:111]
	ds_write_b128 v208, v[44:47]
	ds_write_b128 v208, v[40:43] offset:16
	ds_read_b128 v[216:219], v210
	ds_read_b128 v[220:223], v210 offset:1152
	ds_read_b128 v[48:51], v192 offset:512
	s_waitcnt lgkmcnt(0)
	v_pk_mul_f32 v[36:37], v[46:47], v[50:51]
	v_pk_mul_f32 v[52:53], v[44:45], v[48:49]
	ds_read_b128 v[48:51], v192 offset:528
	s_waitcnt lgkmcnt(0)
	v_pk_mul_f32 v[104:105], v[42:43], v[50:51]
	v_pk_mul_f32 v[50:51], v[40:41], v[48:49]
	v_cvt_pk_bf16_f32 v48, v52, v53
	v_cvt_pk_bf16_f32 v49, v36, v37
	v_cvt_pk_bf16_f32 v50, v50, v51
	v_cvt_pk_bf16_f32 v51, v104, v105
	ds_bpermute_b32 v48, v206, v48
	ds_bpermute_b32 v49, v206, v49
	ds_bpermute_b32 v50, v206, v50
	ds_bpermute_b32 v51, v206, v51
	s_waitcnt lgkmcnt(0)
	global_store_dwordx4 v[28:29], v[48:51], off offset:256
	s_waitcnt lgkmcnt(0)
	global_store_dwordx4 v54, v[216:219], s[20:21] offset:512
	global_store_dwordx4 v54, v[220:223], s[100:101] offset:512
	v_mul_f32_e32 v28, v45, v45
	v_mul_f32_e32 v29, v47, v47
	v_fmac_f32_e32 v28, v44, v44
	v_fmac_f32_e32 v29, v46, v46
	v_add_f32_e32 v28, v28, v29
	v_mul_f32_e32 v29, v41, v41
	v_mul_f32_e32 v36, v43, v43
	v_fmac_f32_e32 v29, v40, v40
	v_fmac_f32_e32 v36, v42, v42
	v_add_f32_e32 v29, v29, v36
	v_and_b32_e32 v36, 64, v242
	v_add_f32_e32 v28, v28, v29
	v_xor_b32_e32 v29, 16, v242
	v_add_u32_e32 v36, 64, v36
	v_cmp_lt_i32_e32 vcc, v29, v36
	v_add_f32_e32 v28, v108, v28
	s_nop 0
	v_cndmask_b32_e32 v29, v242, v29, vcc
	v_lshlrev_b32_e32 v29, 2, v29
	ds_bpermute_b32 v29, v29, v28
	s_waitcnt lgkmcnt(0)
	v_add_f32_e32 v28, v28, v29
	v_xor_b32_e32 v29, 32, v242
	v_cmp_lt_i32_e32 vcc, v29, v36
	s_nop 1
	v_cndmask_b32_e32 v29, v242, v29, vcc
	v_lshlrev_b32_e32 v29, 2, v29
	ds_bpermute_b32 v29, v29, v28
	s_and_saveexec_b64 s[54:55], s[44:45]
	s_cbranch_execz .LBB0_249
	v_lshlrev_b64 v[36:37], 6, v[132:133]
	v_lshl_add_u64 v[36:37], s[22:23], 0, v[36:37]
	v_lshl_add_u64 v[36:37], s[76:77], 2, v[36:37]
	s_lshl_b32 s92, s6, 2
	v_lshl_add_u64 v[36:37], v[36:37], 0, s[92:93]
	s_waitcnt lgkmcnt(0)
	v_add_f32_e32 v28, v28, v29
	global_store_dword v[36:37], v28, off

; #define LAS __attribute__((address_space(3)))
; __device__ __forceinline__ unsigned cvt_pk_bf16(float lo, float hi) { const cvt_f32x2_t v = {lo, hi}; const cvt_bf16x2_t b = __builtin_convertvector(v, cvt_bf16x2_t); return __builtin_bit_cast(unsigned, b); }
; __device__ __forceinline__ float sq4(f32x4 v) { return (v[0] * v[0] + v[1] * v[1]) + (v[2] * v[2] + v[3] * v[3]); }
;     __device__ __forceinline__ void operator()(const f32x4 (&acc)[2][2][4][2], const Unit& u, int wr, int wc, int fr, int fq) const {
;     ...
;             for (int m = 0; m < 4; ++m) {
;                 const int row = u.pm * 256 + ai * 128 + wr * 64 + m * 16 + fr;
;                 const size_t off = (size_t)row * DM + col0;
;                 float ss = 0.f;
; #pragma unroll
;                 for (int bj = 0; bj < 2; ++bj) {
;                     const f32x4 xo0 = xr[m][bj][0] + *(const LAS f32x4*)(gtp + 128 * bj) * acc[ai][bj][m][0], xo1 = xr[m][bj][1] + *(const LAS f32x4*)(gtp + 128 * bj + 4) * acc[ai][bj][m][1];
;                     *(f32x4*)(xout + off + 128 * bj) = xo0; *(f32x4*)(xout + off + 128 * bj + 4) = xo1;
;                     if (gmn) { ss += sq4(xo0) + sq4(xo1); const f32x4 a = xo0 * *(const LAS f32x4*)(gmp + 128 * bj), c = xo1 * *(const LAS f32x4*)(gmp + 128 * bj + 4);
;                         u32x4 w; w.x = cvt_pk_bf16(a[0], a[1]); w.y = cvt_pk_bf16(a[2], a[3]); w.z = cvt_pk_bf16(c[0], c[1]); w.w = cvt_pk_bf16(c[2], c[3]); *(u32x4*)(AX + off + 128 * bj) = w; }
;                 }
;                 if (gmn) { ss += __shfl_xor(ss, 16); ss += __shfl_xor(ss, 32); if (fq == 0) statx[(size_t)row * 16 + u.pn * 4 + wc] = ss; }
.LBB0_252:
	s_waitcnt lgkmcnt(0)
	v_lshlrev_b64 v[28:29], 10, v[130:131]
	v_lshl_add_u64 v[30:31], v[28:29], 0, v[224:225]
	s_waitcnt vmcnt(12)
	v_pk_fma_f32 v[34:35], v[34:35], v[86:87], v[102:103]
	v_pk_fma_f32 v[32:33], v[32:33], v[84:85], v[100:101]
	v_pk_fma_f32 v[38:39], v[26:27], v[78:79], v[98:99]
	v_pk_fma_f32 v[36:37], v[24:25], v[76:77], v[96:97]
	v_lshl_add_u64 v[40:41], v[30:31], 2, s[20:21]
	v_lshl_add_u32 v40, v30, 2, v246
	s_mov_b64 s[54:55], -1
	s_and_b64 vcc, exec, s[46:47]
	s_waitcnt vmcnt(10)
	v_pk_fma_f32 v[28:29], v[20:21], v[60:61], v[92:93]
	v_pk_fma_f32 v[24:25], v[12:13], v[56:57], v[88:89]
	ds_write_b128 v208, v[32:35]
	ds_write_b128 v208, v[36:39] offset:16
	ds_read_b128 v[216:219], v210
	ds_read_b128 v[220:223], v210 offset:1152
	s_cbranch_vccnz .Lxn_ph_5970
	v_mul_f32_e32 v12, v33, v33
	v_mul_f32_e32 v13, v35, v35
	ds_read_b128 v[42:45], v192
	ds_read_b128 v[46:49], v192 offset:16
	v_fmac_f32_e32 v12, v32, v32
	v_fmac_f32_e32 v13, v34, v34
	v_add_f32_e32 v12, v12, v13
	v_mul_f32_e32 v13, v37, v37
	v_mul_f32_e32 v20, v39, v39
	v_fmac_f32_e32 v13, v36, v36
	v_fmac_f32_e32 v20, v38, v38
	v_add_f32_e32 v13, v13, v20
	v_add_f32_e32 v50, v12, v13
	s_waitcnt lgkmcnt(1)
	v_pk_mul_f32 v[12:13], v[34:35], v[44:45]
	v_pk_mul_f32 v[20:21], v[32:33], v[42:43]
	s_waitcnt lgkmcnt(0)
	v_pk_mul_f32 v[26:27], v[38:39], v[48:49]
	v_pk_mul_f32 v[34:35], v[36:37], v[46:47]
	v_cvt_pk_bf16_f32 v32, v20, v21
	v_cvt_pk_bf16_f32 v33, v12, v13
	v_cvt_pk_bf16_f32 v34, v34, v35
	v_cvt_pk_bf16_f32 v35, v26, v27
	v_lshl_add_u64 v[12:13], v[30:31], 1, s[16:17]
	v_lshl_add_u64 v[12:13], v[204:205], 0, v[12:13]
	v_pk_fma_f32 v[30:31], v[22:23], v[62:63], v[94:95]
	ds_bpermute_b32 v32, v206, v32
	ds_bpermute_b32 v33, v206, v33
	ds_bpermute_b32 v34, v206, v34
	ds_bpermute_b32 v35, v206, v35
	s_waitcnt lgkmcnt(0)
	global_store_dwordx4 v[12:13], v[32:35], off
	s_waitcnt lgkmcnt(0)
	global_store_dwordx4 v40, v[216:219], s[20:21]
	global_store_dwordx4 v40, v[220:223], s[100:101]
	v_pk_fma_f32 v[26:27], v[14:15], v[58:59], v[90:91]
	ds_write_b128 v208, v[28:31]
	ds_write_b128 v208, v[24:27] offset:16
	ds_read_b128 v[216:219], v210
	ds_read_b128 v[220:223], v210 offset:1152
	ds_read_b128 v[32:35], v192 offset:512
	s_waitcnt lgkmcnt(0)
	v_pk_mul_f32 v[20:21], v[30:31], v[34:35]
	v_pk_mul_f32 v[36:37], v[28:29], v[32:33]
	ds_read_b128 v[32:35], v192 offset:528
	s_waitcnt lgkmcnt(0)
	v_pk_mul_f32 v[38:39], v[26:27], v[34:35]
	v_pk_mul_f32 v[34:35], v[24:25], v[32:33]
	v_cvt_pk_bf16_f32 v32, v36, v37
	v_cvt_pk_bf16_f32 v33, v20, v21
	v_cvt_pk_bf16_f32 v34, v34, v35
	v_cvt_pk_bf16_f32 v35, v38, v39
	ds_bpermute_b32 v32, v206, v32
	ds_bpermute_b32 v33, v206, v33
	ds_bpermute_b32 v34, v206, v34
	ds_bpermute_b32 v35, v206, v35
	s_waitcnt lgkmcnt(0)
	global_store_dwordx4 v[12:13], v[32:35], off offset:256
	s_waitcnt lgkmcnt(0)
	global_store_dwordx4 v40, v[216:219], s[20:21] offset:512
	global_store_dwordx4 v40, v[220:223], s[100:101] offset:512
	v_mul_f32_e32 v12, v29, v29
	v_mul_f32_e32 v13, v31, v31
	v_fmac_f32_e32 v12, v28, v28
	v_fmac_f32_e32 v13, v30, v30
	v_add_f32_e32 v12, v12, v13
	v_mul_f32_e32 v13, v25, v25
	v_mul_f32_e32 v20, v27, v27
	v_fmac_f32_e32 v13, v24, v24
	v_fmac_f32_e32 v20, v26, v26
	v_add_f32_e32 v13, v13, v20
	v_and_b32_e32 v20, 64, v242
	v_add_f32_e32 v12, v12, v13
	v_xor_b32_e32 v13, 16, v242
	v_add_u32_e32 v20, 64, v20
	v_cmp_lt_i32_e32 vcc, v13, v20
	v_add_f32_e32 v12, v50, v12
	s_nop 0
	v_cndmask_b32_e32 v13, v242, v13, vcc
	v_lshlrev_b32_e32 v13, 2, v13
	ds_bpermute_b32 v13, v13, v12
	s_waitcnt lgkmcnt(0)
	v_add_f32_e32 v12, v12, v13
	v_xor_b32_e32 v13, 32, v242
	v_cmp_lt_i32_e32 vcc, v13, v20
	s_nop 1
	v_cndmask_b32_e32 v13, v242, v13, vcc
	v_lshlrev_b32_e32 v13, 2, v13
	ds_bpermute_b32 v13, v13, v12
	s_and_saveexec_b64 s[54:55], s[44:45]
	s_cbranch_execz .LBB0_255
	v_lshlrev_b64 v[20:21], 6, v[130:131]
	v_lshl_add_u64 v[20:21], s[22:23], 0, v[20:21]
	v_lshl_add_u64 v[20:21], s[76:77], 2, v[20:21]
	s_lshl_b32 s92, s6, 2
	v_lshl_add_u64 v[20:21], v[20:21], 0, s[92:93]
	s_waitcnt lgkmcnt(0)
	v_add_f32_e32 v12, v12, v13
	global_store_dword v[20:21], v12, off

; #define LAS __attribute__((address_space(3)))
;     __device__ __forceinline__ void operator()(const f32x4 (&acc)[2][2][4][2], const Unit& u, int wr, int wc, int fr, int fq) const {
;     ...
;                     const f32x4 xo0 = xr[m][bj][0] + *(const LAS f32x4*)(gtp + 128 * bj) * acc[ai][bj][m][0], xo1 = xr[m][bj][1] + *(const LAS f32x4*)(gtp + 128 * bj + 4) * acc[ai][bj][m][1];
;                     *(f32x4*)(xout + off + 128 * bj) = xo0; *(f32x4*)(xout + off + 128 * bj + 4) = xo1;
.Lxn_ph_5262:
	s_waitcnt lgkmcnt(0)
	global_store_dwordx4 v236, v[216:219], s[20:21]
	global_store_dwordx4 v236, v[220:223], s[100:101]
	s_branch .LBB0_218
.Lxn_ph_5309:
	s_waitcnt lgkmcnt(0)
	global_store_dwordx4 v236, v[216:219], s[20:21] offset:512
	global_store_dwordx4 v236, v[220:223], s[100:101] offset:512
	s_branch .LBB0_222
.Lxn_ph_5378:
	s_waitcnt lgkmcnt(0)
	global_store_dwordx4 v126, v[216:219], s[20:21]
	global_store_dwordx4 v126, v[220:223], s[100:101]
	s_branch .LBB0_226
.Lxn_ph_5488:
	s_waitcnt lgkmcnt(0)
	global_store_dwordx4 v108, v[216:219], s[20:21]
	global_store_dwordx4 v108, v[220:223], s[100:101]
	s_branch .LBB0_232
.Lxn_ph_5597:
	s_waitcnt lgkmcnt(0)
	global_store_dwordx4 v88, v[216:219], s[20:21]
	global_store_dwordx4 v88, v[220:223], s[100:101]
	s_branch .LBB0_238
.Lxn_ph_5744:
	s_waitcnt lgkmcnt(0)
	global_store_dwordx4 v136, v[216:219], s[20:21]
	global_store_dwordx4 v136, v[220:223], s[100:101]
	s_branch .LBB0_242
.Lxn_ph_5787:
	s_waitcnt lgkmcnt(0)
	global_store_dwordx4 v136, v[216:219], s[20:21] offset:512
	global_store_dwordx4 v136, v[220:223], s[100:101] offset:512
	s_branch .LBB0_246
.Lxn_ph_5858:
	s_waitcnt lgkmcnt(0)
	global_store_dwordx4 v54, v[216:219], s[20:21]
	global_store_dwordx4 v54, v[220:223], s[100:101]
	s_branch .LBB0_250
.Lxn_ph_5970:
	s_waitcnt lgkmcnt(0)
	global_store_dwordx4 v40, v[216:219], s[20:21]
	global_store_dwordx4 v40, v[220:223], s[100:101]
	s_branch .LBB0_256

; #define LAS __attribute__((address_space(3)))
; __device__ __forceinline__ unsigned cvt_pk_bf16(float lo, float hi) { const cvt_f32x2_t v = {lo, hi}; const cvt_bf16x2_t b = __builtin_convertvector(v, cvt_bf16x2_t); return __builtin_bit_cast(unsigned, b); }
; __device__ __forceinline__ float sq4(f32x4 v) { return (v[0] * v[0] + v[1] * v[1]) + (v[2] * v[2] + v[3] * v[3]); }
;     __device__ __forceinline__ void operator()(const f32x4 (&acc)[2][2][4][2], const Unit& u, int wr, int wc, int fr, int fq) const {
;     ...
;             for (int m = 0; m < 4; ++m) {
;                 const int row = u.pm * 256 + ai * 128 + wr * 64 + m * 16 + fr;
;                 const size_t off = (size_t)row * DM + col0;
;                 float ss = 0.f;
; #pragma unroll
;                 for (int bj = 0; bj < 2; ++bj) {
;                     const f32x4 xo0 = xr[m][bj][0] + *(const LAS f32x4*)(gtp + 128 * bj) * acc[ai][bj][m][0], xo1 = xr[m][bj][1] + *(const LAS f32x4*)(gtp + 128 * bj + 4) * acc[ai][bj][m][1];
;                     *(f32x4*)(xout + off + 128 * bj) = xo0; *(f32x4*)(xout + off + 128 * bj + 4) = xo1;
;                     if (gmn) { ss += sq4(xo0) + sq4(xo1); const f32x4 a = xo0 * *(const LAS f32x4*)(gmp + 128 * bj), c = xo1 * *(const LAS f32x4*)(gmp + 128 * bj + 4);
;                         u32x4 w; w.x = cvt_pk_bf16(a[0], a[1]); w.y = cvt_pk_bf16(a[2], a[3]); w.z = cvt_pk_bf16(c[0], c[1]); w.w = cvt_pk_bf16(c[2], c[3]); *(u32x4*)(AX + off + 128 * bj) = w; }
;                 }
;                 if (gmn) { ss += __shfl_xor(ss, 16); ss += __shfl_xor(ss, 32); if (fq == 0) statx[(size_t)row * 16 + u.pn * 4 + wc] = ss; }
.LBB0_265:
	v_mul_f32_e32 v0, v17, v17
	v_mul_f32_e32 v1, v19, v19
	ds_read_b128 v[26:29], v192
	ds_read_b128 v[30:33], v192 offset:16
	v_fmac_f32_e32 v0, v16, v16
	v_fmac_f32_e32 v1, v18, v18
	v_add_f32_e32 v0, v0, v1
	v_mul_f32_e32 v1, v21, v21
	v_mul_f32_e32 v4, v23, v23
	v_fmac_f32_e32 v1, v20, v20
	v_fmac_f32_e32 v4, v22, v22
	v_add_f32_e32 v1, v1, v4
	v_add_f32_e32 v34, v0, v1
	s_waitcnt lgkmcnt(1)
	v_pk_mul_f32 v[0:1], v[18:19], v[28:29]
	v_pk_mul_f32 v[4:5], v[16:17], v[26:27]
	s_waitcnt lgkmcnt(0)
	v_pk_mul_f32 v[10:11], v[22:23], v[32:33]
	v_pk_mul_f32 v[18:19], v[20:21], v[30:31]
	v_cvt_pk_bf16_f32 v16, v4, v5
	v_cvt_pk_bf16_f32 v17, v0, v1
	v_cvt_pk_bf16_f32 v18, v18, v19
	v_cvt_pk_bf16_f32 v19, v10, v11
	v_lshl_add_u64 v[0:1], v[14:15], 1, s[16:17]
	v_lshl_add_u64 v[0:1], v[204:205], 0, v[0:1]
	v_pk_fma_f32 v[14:15], v[6:7], v[62:63], v[70:71]
	ds_bpermute_b32 v16, v206, v16
	ds_bpermute_b32 v17, v206, v17
	ds_bpermute_b32 v18, v206, v18
	ds_bpermute_b32 v19, v206, v19
	s_waitcnt lgkmcnt(0)
	global_store_dwordx4 v[0:1], v[16:19], off
	v_pk_fma_f32 v[10:11], v[2:3], v[58:59], v[66:67]
	ds_write_b128 v208, v[12:15]
	ds_write_b128 v208, v[8:11] offset:16
	ds_read_b128 v[216:219], v210
	ds_read_b128 v[220:223], v210 offset:1152
	ds_read_b128 v[16:19], v192 offset:512
	s_waitcnt lgkmcnt(0)
	v_pk_mul_f32 v[4:5], v[14:15], v[18:19]
	v_pk_mul_f32 v[20:21], v[12:13], v[16:17]
	ds_read_b128 v[16:19], v192 offset:528
	s_waitcnt lgkmcnt(0)
	v_pk_mul_f32 v[22:23], v[10:11], v[18:19]
	v_pk_mul_f32 v[18:19], v[8:9], v[16:17]
	v_cvt_pk_bf16_f32 v16, v20, v21
	v_cvt_pk_bf16_f32 v17, v4, v5
	v_cvt_pk_bf16_f32 v18, v18, v19
	v_cvt_pk_bf16_f32 v19, v22, v23
	ds_bpermute_b32 v16, v206, v16
	ds_bpermute_b32 v17, v206, v17
	ds_bpermute_b32 v18, v206, v18
	ds_bpermute_b32 v19, v206, v19
	s_waitcnt lgkmcnt(0)
	global_store_dwordx4 v[0:1], v[16:19], off offset:256
	s_waitcnt lgkmcnt(0)
	global_store_dwordx4 v24, v[216:219], s[20:21] offset:512
	global_store_dwordx4 v24, v[220:223], s[100:101] offset:512
	v_mul_f32_e32 v0, v13, v13
	v_mul_f32_e32 v1, v15, v15
	v_fmac_f32_e32 v0, v12, v12
	v_fmac_f32_e32 v1, v14, v14
	v_add_f32_e32 v0, v0, v1
	v_mul_f32_e32 v1, v9, v9
	v_mul_f32_e32 v4, v11, v11
	v_fmac_f32_e32 v1, v8, v8
	v_fmac_f32_e32 v4, v10, v10
	v_add_f32_e32 v1, v1, v4
	v_and_b32_e32 v4, 64, v242
	v_add_f32_e32 v0, v0, v1
	v_xor_b32_e32 v1, 16, v242
	v_add_u32_e32 v4, 64, v4
	v_cmp_lt_i32_e32 vcc, v1, v4
	v_add_f32_e32 v0, v34, v0
	s_nop 0
	v_cndmask_b32_e32 v1, v242, v1, vcc
	v_lshlrev_b32_e32 v1, 2, v1
	ds_bpermute_b32 v1, v1, v0
	s_waitcnt lgkmcnt(0)
	v_add_f32_e32 v0, v0, v1
	v_xor_b32_e32 v1, 32, v242
	v_cmp_lt_i32_e32 vcc, v1, v4
	s_nop 1
	v_cndmask_b32_e32 v1, v242, v1, vcc
	v_lshlrev_b32_e32 v1, 2, v1
	ds_bpermute_b32 v1, v1, v0
	s_and_saveexec_b64 s[46:47], s[44:45]
	s_cbranch_execz .LBB0_267
	v_lshlrev_b64 v[4:5], 6, v[128:129]
	v_lshl_add_u64 v[4:5], s[22:23], 0, v[4:5]
	v_lshl_add_u64 v[4:5], s[76:77], 2, v[4:5]
	s_lshl_b32 s92, s6, 2
	v_lshl_add_u64 v[4:5], v[4:5], 0, s[92:93]
	s_waitcnt lgkmcnt(0)
	v_add_f32_e32 v0, v0, v1
	global_store_dword v[4:5], v0, off

; __device__ __forceinline__ unsigned cvt_pk_bf16(float lo, float hi) { const cvt_f32x2_t v = {lo, hi}; const cvt_bf16x2_t b = __builtin_convertvector(v, cvt_bf16x2_t); return __builtin_bit_cast(unsigned, b); }
;     __device__ __forceinline__ void operator()(const f32x4 (&acc)[2][2][4][2], const Unit& u, int wr, int wc, int fr, int fq) const {
;     ...
;         for (int ai = 0; ai < 2; ++ai)
; #pragma unroll
;             for (int m = 0; m < 4; ++m) {
;                 const int row = u.pm * 256 + ai * 128 + wr * 64 + m * 16 + fr;
;                 const float rs = rsl[ai * 128 + wr * 64 + m * 16 + fr];
; #pragma unroll
;                 for (int bj = 0; bj < 2; ++bj) {
;                     f32x4 a = acc[ai][bj][m][0] * rs + sw[bj][0], c = acc[ai][bj][m][1] * rs + sw[bj][1];
; #pragma unroll
;                     for (int e = 0; e < 4; ++e) { a[e] = fmaxf(a[e], 0.f); a[e] *= a[e]; c[e] = fmaxf(c[e], 0.f); c[e] *= c[e]; }
;                     u32x4 w; w.x = cvt_pk_bf16(a[0], a[1]); w.y = cvt_pk_bf16(a[2], a[3]); w.z = cvt_pk_bf16(c[0], c[1]); w.w = cvt_pk_bf16(c[2], c[3]);
;                     *(u32x4*)(H + (size_t)row * DFF + col0 + 128 * bj) = w;
;                 }
.LBB0_292:
	s_or_b64 exec, exec, s[44:45]
	v_lshlrev_b32_e32 v163, 2, v154
	s_waitcnt lgkmcnt(0)
	s_barrier
	v_add_u32_e32 v162, s76, v163
	ds_read2_b32 v[164:165], v162 offset1:16
	s_add_i32 s21, s21, s63
	v_add_u32_e32 v154, s21, v154
	v_add_u32_e32 v154, v154, v224
	v_ashrrev_i32_e32 v155, 31, v154
	v_lshlrev_b64 v[166:167], 13, v[154:155]
	s_waitcnt vmcnt(0) lgkmcnt(0)
	v_pk_fma_f32 v[142:143], v[142:143], v[164:165], v[134:135] op_sel_hi:[1,0,1]
	v_pk_fma_f32 v[140:141], v[140:141], v[164:165], v[132:133] op_sel_hi:[1,0,1]
	v_pk_fma_f32 v[136:137], v[136:137], v[164:165], v[128:129] op_sel_hi:[1,0,1]
	v_pk_fma_f32 v[138:139], v[138:139], v[164:165], v[130:131] op_sel_hi:[1,0,1]
	v_max_f32_e32 v140, 0, v140
	v_max_f32_e32 v136, 0, v136
	v_max_f32_e32 v141, 0, v141
	v_max_f32_e32 v137, 0, v137
	v_max_f32_e32 v142, 0, v142
	v_max_f32_e32 v143, 0, v143
	v_pk_mul_f32 v[140:141], v[140:141], v[140:141]
	v_pk_mul_f32 v[136:137], v[136:137], v[136:137]
	v_max_f32_e32 v138, 0, v138
	v_pk_mul_f32 v[142:143], v[142:143], v[142:143]
	v_max_f32_e32 v139, 0, v139
	v_pk_mul_f32 v[168:169], v[138:139], v[138:139]
	v_cvt_pk_bf16_f32 v138, v140, v141
	v_cvt_pk_bf16_f32 v139, v142, v143
	v_cvt_pk_bf16_f32 v140, v136, v137
	v_lshl_add_u64 v[142:143], s[8:9], 0, v[166:167]
	v_add_u32_e32 v156, v156, v227
	v_lshlrev_b64 v[136:137], 1, v[156:157]
	v_pk_fma_f32 v[112:113], v[112:113], v[164:165], v[120:121] op_sel_hi:[1,0,1]
	v_cvt_pk_bf16_f32 v141, v168, v169
	v_lshl_add_u64 v[142:143], v[142:143], 0, v[136:137]
	v_pk_fma_f32 v[118:119], v[118:119], v[164:165], v[126:127] op_sel_hi:[1,0,1]
	v_pk_fma_f32 v[116:117], v[116:117], v[164:165], v[124:125] op_sel_hi:[1,0,1]
	v_pk_fma_f32 v[114:115], v[114:115], v[164:165], v[122:123] op_sel_hi:[1,0,1]
	v_max_f32_e32 v112, 0, v112
	v_max_f32_e32 v113, 0, v113
	ds_bpermute_b32 v228, v226, v138
	ds_bpermute_b32 v229, v226, v139
	ds_bpermute_b32 v230, v226, v140
	ds_bpermute_b32 v231, v226, v141
	v_max_f32_e32 v116, 0, v116
	v_max_f32_e32 v117, 0, v117
	v_pk_mul_f32 v[138:139], v[112:113], v[112:113]
	v_max_f32_e32 v112, 0, v118
	v_max_f32_e32 v114, 0, v114
	v_max_f32_e32 v113, 0, v119
	v_max_f32_e32 v115, 0, v115
	v_pk_mul_f32 v[116:117], v[116:117], v[116:117]
	v_pk_mul_f32 v[118:119], v[112:113], v[112:113]
	v_pk_mul_f32 v[140:141], v[114:115], v[114:115]
	v_cvt_pk_bf16_f32 v112, v116, v117
	v_cvt_pk_bf16_f32 v113, v118, v119
	v_cvt_pk_bf16_f32 v114, v138, v139
	v_cvt_pk_bf16_f32 v115, v140, v141
	ds_bpermute_b32 v232, v226, v112
	ds_bpermute_b32 v233, v226, v113
	ds_bpermute_b32 v234, v226, v114
	ds_bpermute_b32 v235, v226, v115
	s_andn2_b64 vcc, exec, s[42:43]
	s_mov_b64 s[42:43], -1
	v_mov_b32_e32 v114, v165
	v_add_u32_e32 v112, 16, v154
	v_pk_fma_f32 v[108:109], v[108:109], v[114:115], v[132:133] op_sel_hi:[1,0,1]
	v_pk_fma_f32 v[104:105], v[104:105], v[114:115], v[128:129] op_sel_hi:[1,0,1]
	v_ashrrev_i32_e32 v113, 31, v112
	v_pk_fma_f32 v[110:111], v[110:111], v[114:115], v[134:135] op_sel_hi:[1,0,1]
	v_pk_fma_f32 v[106:107], v[106:107], v[114:115], v[130:131] op_sel_hi:[1,0,1]
	v_max_f32_e32 v108, 0, v108
	v_max_f32_e32 v104, 0, v104
	v_max_f32_e32 v109, 0, v109
	v_max_f32_e32 v105, 0, v105
	v_lshlrev_b64 v[112:113], 13, v[112:113]
	v_pk_mul_f32 v[108:109], v[108:109], v[108:109]
	v_pk_mul_f32 v[116:117], v[104:105], v[104:105]
	v_max_f32_e32 v104, 0, v110
	v_max_f32_e32 v106, 0, v106
	v_max_f32_e32 v105, 0, v111
	v_max_f32_e32 v107, 0, v107
	v_pk_mul_f32 v[110:111], v[104:105], v[104:105]
	v_pk_mul_f32 v[118:119], v[106:107], v[106:107]
	v_cvt_pk_bf16_f32 v104, v108, v109
	v_lshl_add_u64 v[108:109], s[8:9], 0, v[112:113]
	v_pk_fma_f32 v[100:101], v[100:101], v[114:115], v[124:125] op_sel_hi:[1,0,1]
	v_pk_fma_f32 v[96:97], v[96:97], v[114:115], v[120:121] op_sel_hi:[1,0,1]
	v_cvt_pk_bf16_f32 v105, v110, v111
	v_cvt_pk_bf16_f32 v106, v116, v117
	v_cvt_pk_bf16_f32 v107, v118, v119
	v_lshl_add_u64 v[108:109], v[108:109], 0, v[136:137]
	v_pk_fma_f32 v[102:103], v[102:103], v[114:115], v[126:127] op_sel_hi:[1,0,1]
	v_max_f32_e32 v100, 0, v100
	v_max_f32_e32 v96, 0, v96
	v_max_f32_e32 v101, 0, v101
	v_max_f32_e32 v97, 0, v97
	s_waitcnt lgkmcnt(4)
	global_store_dwordx4 v[142:143], v[228:231], off
	ds_bpermute_b32 v236, v226, v104
	ds_bpermute_b32 v237, v226, v105
	ds_bpermute_b32 v238, v226, v106
	ds_bpermute_b32 v239, v226, v107
	v_pk_mul_f32 v[100:101], v[100:101], v[100:101]
	v_pk_fma_f32 v[98:99], v[98:99], v[114:115], v[122:123] op_sel_hi:[1,0,1]
	v_pk_mul_f32 v[104:105], v[96:97], v[96:97]
	v_max_f32_e32 v96, 0, v102
	v_max_f32_e32 v97, 0, v103
	v_pk_mul_f32 v[102:103], v[96:97], v[96:97]
	v_cvt_pk_bf16_f32 v96, v100, v101
	ds_read2_b32 v[100:101], v162 offset0:32 offset1:48
	v_max_f32_e32 v98, 0, v98
	v_max_f32_e32 v99, 0, v99
	v_pk_mul_f32 v[106:107], v[98:99], v[98:99]
	v_cvt_pk_bf16_f32 v97, v102, v103
	v_cvt_pk_bf16_f32 v98, v104, v105
	v_cvt_pk_bf16_f32 v99, v106, v107
	s_waitcnt lgkmcnt(4)
	global_store_dwordx4 v[142:143], v[232:235], off offset:256
	ds_bpermute_b32 v228, v226, v96
	ds_bpermute_b32 v229, v226, v97
	ds_bpermute_b32 v230, v226, v98
	ds_bpermute_b32 v231, v226, v99
	s_waitcnt lgkmcnt(0)
; __device__ __forceinline__ unsigned cvt_pk_bf16(float lo, float hi) { const cvt_f32x2_t v = {lo, hi}; const cvt_bf16x2_t b = __builtin_convertvector(v, cvt_bf16x2_t); return __builtin_bit_cast(unsigned, b); }
;     __device__ __forceinline__ void operator()(const f32x4 (&acc)[2][2][4][2], const Unit& u, int wr, int wc, int fr, int fq) const {
;     ...
;         for (int ai = 0; ai < 2; ++ai)
; #pragma unroll
;             for (int m = 0; m < 4; ++m) {
;                 const int row = u.pm * 256 + ai * 128 + wr * 64 + m * 16 + fr;
;                 const float rs = rsl[ai * 128 + wr * 64 + m * 16 + fr];
; #pragma unroll
;                 for (int bj = 0; bj < 2; ++bj) {
;                     f32x4 a = acc[ai][bj][m][0] * rs + sw[bj][0], c = acc[ai][bj][m][1] * rs + sw[bj][1];
; #pragma unroll
;                     for (int e = 0; e < 4; ++e) { a[e] = fmaxf(a[e], 0.f); a[e] *= a[e]; c[e] = fmaxf(c[e], 0.f); c[e] *= c[e]; }
;                     u32x4 w; w.x = cvt_pk_bf16(a[0], a[1]); w.y = cvt_pk_bf16(a[2], a[3]); w.z = cvt_pk_bf16(c[0], c[1]); w.w = cvt_pk_bf16(c[2], c[3]);
;                     *(u32x4*)(H + (size_t)row * DFF + col0 + 128 * bj) = w;
;                 }
	v_pk_fma_f32 v[92:93], v[92:93], v[100:101], v[132:133] op_sel_hi:[1,0,1]
	v_pk_fma_f32 v[88:89], v[88:89], v[100:101], v[128:129] op_sel_hi:[1,0,1]
	v_add_u32_e32 v96, 32, v154
	v_ashrrev_i32_e32 v97, 31, v96
	v_pk_fma_f32 v[94:95], v[94:95], v[100:101], v[134:135] op_sel_hi:[1,0,1]
	v_pk_fma_f32 v[90:91], v[90:91], v[100:101], v[130:131] op_sel_hi:[1,0,1]
	v_max_f32_e32 v92, 0, v92
	v_max_f32_e32 v88, 0, v88
	v_max_f32_e32 v93, 0, v93
	v_max_f32_e32 v89, 0, v89
	v_lshlrev_b64 v[96:97], 13, v[96:97]
	v_pk_mul_f32 v[92:93], v[92:93], v[92:93]
	v_pk_mul_f32 v[98:99], v[88:89], v[88:89]
	v_max_f32_e32 v88, 0, v94
	v_max_f32_e32 v90, 0, v90
	v_max_f32_e32 v89, 0, v95
	v_max_f32_e32 v91, 0, v91
	v_pk_mul_f32 v[94:95], v[88:89], v[88:89]
	v_pk_mul_f32 v[102:103], v[90:91], v[90:91]
	v_cvt_pk_bf16_f32 v88, v92, v93
	v_lshl_add_u64 v[92:93], s[8:9], 0, v[96:97]
	v_pk_fma_f32 v[80:81], v[80:81], v[100:101], v[120:121] op_sel_hi:[1,0,1]
	v_cvt_pk_bf16_f32 v89, v94, v95
	v_cvt_pk_bf16_f32 v90, v98, v99
	v_cvt_pk_bf16_f32 v91, v102, v103
	v_lshl_add_u64 v[92:93], v[92:93], 0, v[136:137]
	v_pk_fma_f32 v[86:87], v[86:87], v[100:101], v[126:127] op_sel_hi:[1,0,1]
	v_pk_fma_f32 v[84:85], v[84:85], v[100:101], v[124:125] op_sel_hi:[1,0,1]
	v_pk_fma_f32 v[82:83], v[82:83], v[100:101], v[122:123] op_sel_hi:[1,0,1]
	v_max_f32_e32 v80, 0, v80
	v_max_f32_e32 v81, 0, v81
	s_waitcnt lgkmcnt(4)
	global_store_dwordx4 v[108:109], v[236:239], off
	ds_bpermute_b32 v232, v226, v88
	ds_bpermute_b32 v233, v226, v89
	ds_bpermute_b32 v234, v226, v90
	ds_bpermute_b32 v235, v226, v91
	v_max_f32_e32 v84, 0, v84
	v_max_f32_e32 v85, 0, v85
	v_pk_mul_f32 v[88:89], v[80:81], v[80:81]
	v_max_f32_e32 v80, 0, v86
	v_max_f32_e32 v82, 0, v82
	v_max_f32_e32 v81, 0, v87
	v_max_f32_e32 v83, 0, v83
	v_pk_mul_f32 v[84:85], v[84:85], v[84:85]
	v_pk_mul_f32 v[86:87], v[80:81], v[80:81]
	v_pk_mul_f32 v[90:91], v[82:83], v[82:83]
	v_cvt_pk_bf16_f32 v80, v84, v85
	v_cvt_pk_bf16_f32 v81, v86, v87
	v_cvt_pk_bf16_f32 v82, v88, v89
	v_cvt_pk_bf16_f32 v83, v90, v91
	s_waitcnt lgkmcnt(4)
	global_store_dwordx4 v[108:109], v[228:231], off offset:256
	ds_bpermute_b32 v236, v226, v80
	ds_bpermute_b32 v237, v226, v81
	ds_bpermute_b32 v238, v226, v82
	ds_bpermute_b32 v239, v226, v83
	s_nop 1
	v_mov_b32_e32 v82, v101
	v_add_u32_e32 v80, 48, v154
	v_pk_fma_f32 v[76:77], v[76:77], v[82:83], v[132:133] op_sel_hi:[1,0,1]
	v_pk_fma_f32 v[72:73], v[72:73], v[82:83], v[128:129] op_sel_hi:[1,0,1]
	v_ashrrev_i32_e32 v81, 31, v80
	v_pk_fma_f32 v[78:79], v[78:79], v[82:83], v[134:135] op_sel_hi:[1,0,1]
	v_pk_fma_f32 v[74:75], v[74:75], v[82:83], v[130:131] op_sel_hi:[1,0,1]
	v_max_f32_e32 v76, 0, v76
	v_max_f32_e32 v72, 0, v72
	v_max_f32_e32 v77, 0, v77
	v_max_f32_e32 v73, 0, v73
	v_lshlrev_b64 v[80:81], 13, v[80:81]
	v_pk_mul_f32 v[76:77], v[76:77], v[76:77]
	v_pk_mul_f32 v[84:85], v[72:73], v[72:73]
	v_max_f32_e32 v72, 0, v78
	v_max_f32_e32 v74, 0, v74
	v_max_f32_e32 v73, 0, v79
	v_max_f32_e32 v75, 0, v75
	v_pk_mul_f32 v[78:79], v[72:73], v[72:73]
	v_pk_mul_f32 v[86:87], v[74:75], v[74:75]
	v_cvt_pk_bf16_f32 v72, v76, v77
	v_lshl_add_u64 v[76:77], s[8:9], 0, v[80:81]
	v_pk_fma_f32 v[64:65], v[64:65], v[82:83], v[120:121] op_sel_hi:[1,0,1]
	v_cvt_pk_bf16_f32 v73, v78, v79
	v_cvt_pk_bf16_f32 v74, v84, v85
	v_cvt_pk_bf16_f32 v75, v86, v87
	v_lshl_add_u64 v[76:77], v[76:77], 0, v[136:137]
	v_pk_fma_f32 v[70:71], v[70:71], v[82:83], v[126:127] op_sel_hi:[1,0,1]
	v_pk_fma_f32 v[68:69], v[68:69], v[82:83], v[124:125] op_sel_hi:[1,0,1]
	v_pk_fma_f32 v[66:67], v[66:67], v[82:83], v[122:123] op_sel_hi:[1,0,1]
	v_max_f32_e32 v64, 0, v64
	v_max_f32_e32 v65, 0, v65
	s_waitcnt lgkmcnt(4)
	global_store_dwordx4 v[92:93], v[232:235], off
	ds_bpermute_b32 v228, v226, v72
	ds_bpermute_b32 v229, v226, v73
	ds_bpermute_b32 v230, v226, v74
	ds_bpermute_b32 v231, v226, v75
	v_max_f32_e32 v68, 0, v68
	v_max_f32_e32 v69, 0, v69
	v_pk_mul_f32 v[72:73], v[64:65], v[64:65]
	v_max_f32_e32 v64, 0, v70
	v_max_f32_e32 v66, 0, v66
	v_max_f32_e32 v65, 0, v71
	v_max_f32_e32 v67, 0, v67
	v_pk_mul_f32 v[68:69], v[68:69], v[68:69]
	v_pk_mul_f32 v[70:71], v[64:65], v[64:65]
	v_pk_mul_f32 v[74:75], v[66:67], v[66:67]
	v_cvt_pk_bf16_f32 v64, v68, v69
	v_cvt_pk_bf16_f32 v65, v70, v71
	v_cvt_pk_bf16_f32 v66, v72, v73
	v_cvt_pk_bf16_f32 v67, v74, v75
	s_waitcnt lgkmcnt(4)
	global_store_dwordx4 v[92:93], v[236:239], off offset:256
	ds_bpermute_b32 v232, v226, v64
	ds_bpermute_b32 v233, v226, v65
	ds_bpermute_b32 v234, v226, v66
	ds_bpermute_b32 v235, v226, v67
	ds_read_b32 v68, v162 offset:704
	s_waitcnt lgkmcnt(0)
	v_pk_fma_f32 v[8:9], v[8:9], v[68:69], v[128:129] op_sel_hi:[1,0,1]
	v_add_u32_e32 v64, s77, v163
	ds_read_b32 v64, v64
	v_add_u32_e32 v66, 0x80, v154
	v_ashrrev_i32_e32 v67, 31, v66
	v_lshlrev_b64 v[66:67], 13, v[66:67]
	v_pk_fma_f32 v[16:17], v[16:17], v[68:69], v[132:133] op_sel_hi:[1,0,1]
	s_waitcnt lgkmcnt(0)
	v_pk_fma_f32 v[60:61], v[60:61], v[64:65], v[132:133] op_sel_hi:[1,0,1]
	v_pk_fma_f32 v[56:57], v[56:57], v[64:65], v[128:129] op_sel_hi:[1,0,1]
	v_pk_fma_f32 v[62:63], v[62:63], v[64:65], v[134:135] op_sel_hi:[1,0,1]
	v_pk_fma_f32 v[58:59], v[58:59], v[64:65], v[130:131] op_sel_hi:[1,0,1]
	v_max_f32_e32 v60, 0, v60
	v_max_f32_e32 v56, 0, v56
	v_max_f32_e32 v61, 0, v61
	v_max_f32_e32 v57, 0, v57
	v_pk_mul_f32 v[60:61], v[60:61], v[60:61]
	v_pk_mul_f32 v[70:71], v[56:57], v[56:57]
	v_max_f32_e32 v56, 0, v62
	v_max_f32_e32 v58, 0, v58
	v_max_f32_e32 v57, 0, v63
	v_max_f32_e32 v59, 0, v59
	v_pk_mul_f32 v[62:63], v[56:57], v[56:57]
	v_pk_mul_f32 v[72:73], v[58:59], v[58:59]
	v_cvt_pk_bf16_f32 v56, v60, v61
	v_lshl_add_u64 v[60:61], s[8:9], 0, v[66:67]
	v_pk_fma_f32 v[52:53], v[52:53], v[64:65], v[124:125] op_sel_hi:[1,0,1]
	v_pk_fma_f32 v[44:45], v[44:45], v[64:65], v[120:121] op_sel_hi:[1,0,1]
	v_cvt_pk_bf16_f32 v57, v62, v63
	v_cvt_pk_bf16_f32 v58, v70, v71
	v_cvt_pk_bf16_f32 v59, v72, v73
	v_lshl_add_u64 v[60:61], v[60:61], 0, v[136:137]
	v_pk_fma_f32 v[54:55], v[54:55], v[64:65], v[126:127] op_sel_hi:[1,0,1]
	v_max_f32_e32 v52, 0, v52
	v_max_f32_e32 v44, 0, v44
	v_max_f32_e32 v53, 0, v53
	v_max_f32_e32 v45, 0, v45
	s_waitcnt lgkmcnt(4)
; __device__ __forceinline__ unsigned cvt_pk_bf16(float lo, float hi) { const cvt_f32x2_t v = {lo, hi}; const cvt_bf16x2_t b = __builtin_convertvector(v, cvt_bf16x2_t); return __builtin_bit_cast(unsigned, b); }
;     __device__ __forceinline__ void operator()(const f32x4 (&acc)[2][2][4][2], const Unit& u, int wr, int wc, int fr, int fq) const {
;     ...
;         for (int ai = 0; ai < 2; ++ai)
; #pragma unroll
;             for (int m = 0; m < 4; ++m) {
;                 const int row = u.pm * 256 + ai * 128 + wr * 64 + m * 16 + fr;
;                 const float rs = rsl[ai * 128 + wr * 64 + m * 16 + fr];
; #pragma unroll
;                 for (int bj = 0; bj < 2; ++bj) {
;                     f32x4 a = acc[ai][bj][m][0] * rs + sw[bj][0], c = acc[ai][bj][m][1] * rs + sw[bj][1];
; #pragma unroll
;                     for (int e = 0; e < 4; ++e) { a[e] = fmaxf(a[e], 0.f); a[e] *= a[e]; c[e] = fmaxf(c[e], 0.f); c[e] *= c[e]; }
;                     u32x4 w; w.x = cvt_pk_bf16(a[0], a[1]); w.y = cvt_pk_bf16(a[2], a[3]); w.z = cvt_pk_bf16(c[0], c[1]); w.w = cvt_pk_bf16(c[2], c[3]);
;                     *(u32x4*)(H + (size_t)row * DFF + col0 + 128 * bj) = w;
;                 }
	global_store_dwordx4 v[76:77], v[228:231], off
	ds_bpermute_b32 v236, v226, v56
	ds_bpermute_b32 v237, v226, v57
	ds_bpermute_b32 v238, v226, v58
	ds_bpermute_b32 v239, v226, v59
	v_pk_mul_f32 v[52:53], v[52:53], v[52:53]
	v_pk_fma_f32 v[46:47], v[46:47], v[64:65], v[122:123] op_sel_hi:[1,0,1]
	v_pk_mul_f32 v[56:57], v[44:45], v[44:45]
	v_max_f32_e32 v44, 0, v54
	v_max_f32_e32 v45, 0, v55
	v_pk_mul_f32 v[54:55], v[44:45], v[44:45]
	v_cvt_pk_bf16_f32 v44, v52, v53
	ds_read2_b32 v[52:53], v162 offset0:144 offset1:160
	v_max_f32_e32 v46, 0, v46
	v_max_f32_e32 v47, 0, v47
	v_pk_mul_f32 v[58:59], v[46:47], v[46:47]
	v_cvt_pk_bf16_f32 v45, v54, v55
	v_cvt_pk_bf16_f32 v46, v56, v57
	v_cvt_pk_bf16_f32 v47, v58, v59
	s_waitcnt lgkmcnt(4)
	global_store_dwordx4 v[76:77], v[232:235], off offset:256
	ds_bpermute_b32 v228, v226, v44
	ds_bpermute_b32 v229, v226, v45
	ds_bpermute_b32 v230, v226, v46
	ds_bpermute_b32 v231, v226, v47
	s_waitcnt lgkmcnt(0)
	v_pk_fma_f32 v[40:41], v[40:41], v[52:53], v[128:129] op_sel_hi:[1,0,1]
	v_pk_fma_f32 v[48:49], v[48:49], v[52:53], v[132:133] op_sel_hi:[1,0,1]
	v_add_u32_e32 v44, 0x90, v154
	v_ashrrev_i32_e32 v45, 31, v44
	v_pk_fma_f32 v[46:47], v[50:51], v[52:53], v[134:135] op_sel_hi:[1,0,1]
	v_pk_fma_f32 v[42:43], v[42:43], v[52:53], v[130:131] op_sel_hi:[1,0,1]
	v_max_f32_e32 v40, 0, v40
	v_max_f32_e32 v41, 0, v41
	v_lshlrev_b64 v[44:45], 13, v[44:45]
	v_max_f32_e32 v48, 0, v48
	v_max_f32_e32 v49, 0, v49
	v_pk_mul_f32 v[50:51], v[40:41], v[40:41]
	v_max_f32_e32 v40, 0, v46
	v_max_f32_e32 v42, 0, v42
	v_max_f32_e32 v41, 0, v47
	v_max_f32_e32 v43, 0, v43
	v_pk_mul_f32 v[48:49], v[48:49], v[48:49]
	v_pk_mul_f32 v[46:47], v[40:41], v[40:41]
	v_pk_mul_f32 v[54:55], v[42:43], v[42:43]
	v_lshl_add_u64 v[44:45], s[8:9], 0, v[44:45]
	v_pk_fma_f32 v[28:29], v[28:29], v[52:53], v[120:121] op_sel_hi:[1,0,1]
	v_cvt_pk_bf16_f32 v40, v48, v49
	v_cvt_pk_bf16_f32 v41, v46, v47
	v_cvt_pk_bf16_f32 v42, v50, v51
	v_cvt_pk_bf16_f32 v43, v54, v55
	v_lshl_add_u64 v[44:45], v[44:45], 0, v[136:137]
	v_pk_fma_f32 v[38:39], v[38:39], v[52:53], v[126:127] op_sel_hi:[1,0,1]
	v_pk_fma_f32 v[36:37], v[36:37], v[52:53], v[124:125] op_sel_hi:[1,0,1]
	v_pk_fma_f32 v[30:31], v[30:31], v[52:53], v[122:123] op_sel_hi:[1,0,1]
	v_max_f32_e32 v28, 0, v28
	v_max_f32_e32 v29, 0, v29
	s_waitcnt lgkmcnt(4)
	global_store_dwordx4 v[60:61], v[236:239], off
	ds_bpermute_b32 v232, v226, v40
	ds_bpermute_b32 v233, v226, v41
	ds_bpermute_b32 v234, v226, v42
	ds_bpermute_b32 v235, v226, v43
	v_max_f32_e32 v36, 0, v36
	v_max_f32_e32 v37, 0, v37
	v_pk_mul_f32 v[40:41], v[28:29], v[28:29]
	v_max_f32_e32 v28, 0, v38
	v_max_f32_e32 v30, 0, v30
	v_max_f32_e32 v29, 0, v39
	v_max_f32_e32 v31, 0, v31
	v_pk_mul_f32 v[36:37], v[36:37], v[36:37]
	v_pk_mul_f32 v[38:39], v[28:29], v[28:29]
	v_pk_mul_f32 v[42:43], v[30:31], v[30:31]
	v_cvt_pk_bf16_f32 v28, v36, v37
	v_cvt_pk_bf16_f32 v29, v38, v39
	v_cvt_pk_bf16_f32 v30, v40, v41
	v_cvt_pk_bf16_f32 v31, v42, v43
	s_waitcnt lgkmcnt(4)
	global_store_dwordx4 v[60:61], v[228:231], off offset:256
	ds_bpermute_b32 v236, v226, v28
	ds_bpermute_b32 v237, v226, v29
	ds_bpermute_b32 v238, v226, v30
	ds_bpermute_b32 v239, v226, v31
	v_pk_fma_f32 v[10:11], v[10:11], v[68:69], v[130:131] op_sel_hi:[1,0,1]
	v_max_f32_e32 v8, 0, v8
	v_mov_b32_e32 v30, v53
	v_add_u32_e32 v28, 0xa0, v154
	v_pk_fma_f32 v[24:25], v[24:25], v[30:31], v[128:129] op_sel_hi:[1,0,1]
	v_ashrrev_i32_e32 v29, 31, v28
	v_pk_fma_f32 v[34:35], v[34:35], v[30:31], v[134:135] op_sel_hi:[1,0,1]
	v_pk_fma_f32 v[32:33], v[32:33], v[30:31], v[132:133] op_sel_hi:[1,0,1]
	v_pk_fma_f32 v[26:27], v[26:27], v[30:31], v[130:131] op_sel_hi:[1,0,1]
	v_max_f32_e32 v24, 0, v24
	v_max_f32_e32 v25, 0, v25
	v_lshlrev_b64 v[28:29], 13, v[28:29]
	v_max_f32_e32 v32, 0, v32
	v_max_f32_e32 v33, 0, v33
	v_pk_mul_f32 v[36:37], v[24:25], v[24:25]
	v_max_f32_e32 v24, 0, v34
	v_max_f32_e32 v26, 0, v26
	v_max_f32_e32 v25, 0, v35
	v_max_f32_e32 v27, 0, v27
	v_pk_mul_f32 v[32:33], v[32:33], v[32:33]
	v_pk_mul_f32 v[34:35], v[24:25], v[24:25]
	v_pk_mul_f32 v[38:39], v[26:27], v[26:27]
	v_lshl_add_u64 v[28:29], s[8:9], 0, v[28:29]
	v_pk_fma_f32 v[12:13], v[12:13], v[30:31], v[120:121] op_sel_hi:[1,0,1]
	v_cvt_pk_bf16_f32 v24, v32, v33
	v_cvt_pk_bf16_f32 v25, v34, v35
	v_cvt_pk_bf16_f32 v26, v36, v37
	v_cvt_pk_bf16_f32 v27, v38, v39
	v_lshl_add_u64 v[28:29], v[28:29], 0, v[136:137]
	v_pk_fma_f32 v[22:23], v[22:23], v[30:31], v[126:127] op_sel_hi:[1,0,1]
	v_pk_fma_f32 v[20:21], v[20:21], v[30:31], v[124:125] op_sel_hi:[1,0,1]
	v_pk_fma_f32 v[14:15], v[14:15], v[30:31], v[122:123] op_sel_hi:[1,0,1]
	v_max_f32_e32 v12, 0, v12
	v_max_f32_e32 v13, 0, v13
	s_waitcnt lgkmcnt(4)
; __device__ __forceinline__ unsigned cvt_pk_bf16(float lo, float hi) { const cvt_f32x2_t v = {lo, hi}; const cvt_bf16x2_t b = __builtin_convertvector(v, cvt_bf16x2_t); return __builtin_bit_cast(unsigned, b); }
;     __device__ __forceinline__ void operator()(const f32x4 (&acc)[2][2][4][2], const Unit& u, int wr, int wc, int fr, int fq) const {
;     ...
;         for (int ai = 0; ai < 2; ++ai)
; #pragma unroll
;             for (int m = 0; m < 4; ++m) {
;                 const int row = u.pm * 256 + ai * 128 + wr * 64 + m * 16 + fr;
;                 const float rs = rsl[ai * 128 + wr * 64 + m * 16 + fr];
; #pragma unroll
;                 for (int bj = 0; bj < 2; ++bj) {
;                     f32x4 a = acc[ai][bj][m][0] * rs + sw[bj][0], c = acc[ai][bj][m][1] * rs + sw[bj][1];
; #pragma unroll
;                     for (int e = 0; e < 4; ++e) { a[e] = fmaxf(a[e], 0.f); a[e] *= a[e]; c[e] = fmaxf(c[e], 0.f); c[e] *= c[e]; }
;                     u32x4 w; w.x = cvt_pk_bf16(a[0], a[1]); w.y = cvt_pk_bf16(a[2], a[3]); w.z = cvt_pk_bf16(c[0], c[1]); w.w = cvt_pk_bf16(c[2], c[3]);
;                     *(u32x4*)(H + (size_t)row * DFF + col0 + 128 * bj) = w;
;                 }
	global_store_dwordx4 v[44:45], v[232:235], off
	ds_bpermute_b32 v228, v226, v24
	ds_bpermute_b32 v229, v226, v25
	ds_bpermute_b32 v230, v226, v26
	ds_bpermute_b32 v231, v226, v27
	v_max_f32_e32 v20, 0, v20
	v_max_f32_e32 v21, 0, v21
	v_pk_mul_f32 v[24:25], v[12:13], v[12:13]
	v_max_f32_e32 v12, 0, v22
	v_max_f32_e32 v14, 0, v14
	v_max_f32_e32 v13, 0, v23
	v_max_f32_e32 v15, 0, v15
	v_pk_mul_f32 v[20:21], v[20:21], v[20:21]
	v_pk_mul_f32 v[22:23], v[12:13], v[12:13]
	v_pk_mul_f32 v[26:27], v[14:15], v[14:15]
	v_cvt_pk_bf16_f32 v12, v20, v21
	v_cvt_pk_bf16_f32 v13, v22, v23
	v_cvt_pk_bf16_f32 v14, v24, v25
	v_cvt_pk_bf16_f32 v15, v26, v27
	s_waitcnt lgkmcnt(4)
	global_store_dwordx4 v[44:45], v[236:239], off offset:256
	ds_bpermute_b32 v232, v226, v12
	ds_bpermute_b32 v233, v226, v13
	ds_bpermute_b32 v234, v226, v14
	ds_bpermute_b32 v235, v226, v15
	v_max_f32_e32 v9, 0, v9
	v_max_f32_e32 v16, 0, v16
	v_add_u32_e32 v12, 0xb0, v154
	v_ashrrev_i32_e32 v13, 31, v12
	v_pk_fma_f32 v[14:15], v[18:19], v[68:69], v[134:135] op_sel_hi:[1,0,1]
	v_lshlrev_b64 v[12:13], 13, v[12:13]
	v_max_f32_e32 v17, 0, v17
	v_pk_mul_f32 v[18:19], v[8:9], v[8:9]
	v_max_f32_e32 v8, 0, v14
	v_max_f32_e32 v10, 0, v10
	v_max_f32_e32 v9, 0, v15
	v_max_f32_e32 v11, 0, v11
	v_pk_mul_f32 v[16:17], v[16:17], v[16:17]
	v_pk_mul_f32 v[14:15], v[8:9], v[8:9]
	v_pk_mul_f32 v[20:21], v[10:11], v[10:11]
	v_lshl_add_u64 v[12:13], s[8:9], 0, v[12:13]
	v_pk_fma_f32 v[0:1], v[0:1], v[68:69], v[120:121] op_sel_hi:[1,0,1]
	v_cvt_pk_bf16_f32 v8, v16, v17
	v_cvt_pk_bf16_f32 v9, v14, v15
	v_cvt_pk_bf16_f32 v10, v18, v19
	v_cvt_pk_bf16_f32 v11, v20, v21
	v_lshl_add_u64 v[12:13], v[12:13], 0, v[136:137]
	v_pk_fma_f32 v[6:7], v[6:7], v[68:69], v[126:127] op_sel_hi:[1,0,1]
	v_pk_fma_f32 v[4:5], v[4:5], v[68:69], v[124:125] op_sel_hi:[1,0,1]
	v_pk_fma_f32 v[2:3], v[2:3], v[68:69], v[122:123] op_sel_hi:[1,0,1]
	v_max_f32_e32 v0, 0, v0
	v_max_f32_e32 v1, 0, v1
	s_waitcnt lgkmcnt(4)
	global_store_dwordx4 v[28:29], v[228:231], off
	ds_bpermute_b32 v236, v226, v8
	ds_bpermute_b32 v237, v226, v9
	ds_bpermute_b32 v238, v226, v10
	ds_bpermute_b32 v239, v226, v11
	v_max_f32_e32 v4, 0, v4
	v_max_f32_e32 v5, 0, v5
	v_pk_mul_f32 v[8:9], v[0:1], v[0:1]
	v_max_f32_e32 v0, 0, v6
	v_max_f32_e32 v2, 0, v2
	v_max_f32_e32 v1, 0, v7
	v_max_f32_e32 v3, 0, v3
	v_pk_mul_f32 v[4:5], v[4:5], v[4:5]
	v_pk_mul_f32 v[6:7], v[0:1], v[0:1]
	v_pk_mul_f32 v[10:11], v[2:3], v[2:3]
	v_cvt_pk_bf16_f32 v0, v4, v5
	v_cvt_pk_bf16_f32 v1, v6, v7
	v_cvt_pk_bf16_f32 v2, v8, v9
	v_cvt_pk_bf16_f32 v3, v10, v11
	s_waitcnt lgkmcnt(4)
	global_store_dwordx4 v[28:29], v[232:235], off offset:256
	ds_bpermute_b32 v228, v226, v0
	ds_bpermute_b32 v229, v226, v1
	ds_bpermute_b32 v230, v226, v2
	ds_bpermute_b32 v231, v226, v3
	s_waitcnt lgkmcnt(4)
	global_store_dwordx4 v[12:13], v[236:239], off
	s_waitcnt lgkmcnt(0)
	global_store_dwordx4 v[12:13], v[228:231], off offset:256
	s_cbranch_vccnz .LBB0_279
	v_readlane_b32 s4, v255, 46
	v_readlane_b32 s5, v255, 47
	s_andn2_b64 vcc, exec, s[4:5]
	s_cbranch_vccnz .LBB0_278
	s_barrier
	s_branch .LBB0_278

;     __device__ __forceinline__ void operator()(const f32x4 (&acc)[2][2][4][2], const Unit& u, int wr, int wc, int fr, int fq) const {
;         const int b = u.pm >> 3, col0 = u.pn * 256 + wc * 32 + 8 * fq;
;         { const int t = (wr * 4 + wc) * 64 + fq * 16 + fr;
;           if (t < 64) ((LAS f32x4*)gl)[t] = *(const f32x4*)(gate + (size_t)b * gate_ld + u.pn * 256 + 4 * t);
;           else if (t < 128 && gmn) ((LAS f32x4*)gl)[t] = *(const f32x4*)(gmn + (size_t)b * DM + u.pn * 256 + 4 * (t - 64));
;           asm volatile("s_waitcnt vmcnt(0) lgkmcnt(0)" ::: "memory"); __builtin_amdgcn_s_barrier(); asm volatile("" ::: "memory"); }
;         const LAS float* gtp = gl + wc * 32 + 8 * fq; const LAS float* gmp = gl + 256 + wc * 32 + 8 * fq;
; #pragma unroll
;         for (int ai = 0; ai < 2; ++ai) {
;             f32x4 xr[4][2][2];
; #pragma unroll
;             for (int m = 0; m < 4; ++m) { const size_t off = (size_t)(u.pm * 256 + ai * 128 + wr * 64 + m * 16 + fr) * DM + col0;
; #pragma unroll
;                 for (int bj = 0; bj < 2; ++bj)
; #pragma unroll
;                     for (int n = 0; n < 2; ++n) xr[m][bj][n] = *(const f32x4*)(xin + off + 128 * bj + 4 * n); }
;             asm volatile("" ::: "memory");
; #pragma unroll
;             for (int m = 0; m < 4; ++m) {
;                 const int row = u.pm * 256 + ai * 128 + wr * 64 + m * 16 + fr;
;                 const size_t off = (size_t)row * DM + col0;
;                 float ss = 0.f;
; #pragma unroll
;                 for (int bj = 0; bj < 2; ++bj) {
;                     const f32x4 xo0 = xr[m][bj][0] + *(const LAS f32x4*)(gtp + 128 * bj) * acc[ai][bj][m][0], xo1 = xr[m][bj][1] + *(const LAS f32x4*)(gtp + 128 * bj + 4) * acc[ai][bj][m][1];
;                     *(f32x4*)(xout + off + 128 * bj) = xo0; *(f32x4*)(xout + off + 128 * bj + 4) = xo1;
;                     if (gmn) { ss += sq4(xo0) + sq4(xo1); const f32x4 a = xo0 * *(const LAS f32x4*)(gmp + 128 * bj), c = xo1 * *(const LAS f32x4*)(gmp + 128 * bj + 4);
;                         u32x4 w; w.x = cvt_pk_bf16(a[0], a[1]); w.y = cvt_pk_bf16(a[2], a[3]); w.z = cvt_pk_bf16(c[0], c[1]); w.w = cvt_pk_bf16(c[2], c[3]); *(u32x4*)(AX + off + 128 * bj) = w; }
;                 }
;                 if (gmn) { ss += __shfl_xor(ss, 16); ss += __shfl_xor(ss, 32); if (fq == 0) statx[(size_t)row * 16 + u.pn * 4 + wc] = ss; }
.LBB0_323:
	s_or_b64 exec, exec, s[46:47]
	s_or_b32 s44, s44, s9
	v_lshl_add_u32 v224, v250, 3, s44
	s_lshl_b32 s44, s77, 8
	s_add_i32 s44, s44, s8
	v_add_u32_e32 v226, s44, v106
	v_readlane_b32 s44, v255, 48
	v_lshlrev_b32_e32 v104, 5, v250
	v_ashrrev_i32_e32 v225, 31, v224
	v_readlane_b32 s45, v255, 49
	v_ashrrev_i32_e32 v227, 31, v226
	v_add_u32_e32 v249, s41, v104
	v_add_u32_e32 v192, s4, v104
	v_lshl_add_u64 v[228:229], v[224:225], 2, s[44:45]
	v_lshlrev_b64 v[104:105], 12, v[226:227]
	v_add_u32_e32 v234, 16, v226
	s_waitcnt vmcnt(0) lgkmcnt(0)
	s_barrier
	v_lshl_add_u64 v[104:105], v[228:229], 0, v[104:105]
	v_ashrrev_i32_e32 v235, 31, v234
	global_load_dwordx4 v[194:197], v[104:105], off offset:16
	global_load_dwordx4 v[198:201], v[104:105], off
	global_load_dwordx4 v[184:187], v[104:105], off offset:528
	global_load_dwordx4 v[188:191], v[104:105], off offset:512
	v_lshlrev_b64 v[104:105], 12, v[234:235]
	v_add_u32_e32 v232, 32, v226
	v_lshl_add_u64 v[104:105], v[228:229], 0, v[104:105]
	v_ashrrev_i32_e32 v233, 31, v232
	global_load_dwordx4 v[176:179], v[104:105], off offset:16
	global_load_dwordx4 v[180:183], v[104:105], off
	global_load_dwordx4 v[168:171], v[104:105], off offset:528
	global_load_dwordx4 v[172:175], v[104:105], off offset:512
	v_lshlrev_b64 v[104:105], 12, v[232:233]
	v_add_u32_e32 v230, 48, v226
	v_lshl_add_u64 v[104:105], v[228:229], 0, v[104:105]
	v_ashrrev_i32_e32 v231, 31, v230
	global_load_dwordx4 v[160:163], v[104:105], off offset:16
	global_load_dwordx4 v[164:167], v[104:105], off
	global_load_dwordx4 v[152:155], v[104:105], off offset:528
	global_load_dwordx4 v[156:159], v[104:105], off offset:512
	v_lshlrev_b64 v[104:105], 12, v[230:231]
	v_lshl_add_u64 v[112:113], v[228:229], 0, v[104:105]
	global_load_dwordx4 v[136:139], v[112:113], off offset:16
	global_load_dwordx4 v[144:147], v[112:113], off
	global_load_dwordx4 v[104:107], v[112:113], off offset:528
	s_nop 0
	global_load_dwordx4 v[112:115], v[112:113], off offset:512
	v_lshlrev_b64 v[140:141], 10, v[226:227]
	v_lshl_add_u64 v[202:203], v[140:141], 0, v[224:225]
	ds_read_b128 v[148:151], v249
	ds_read_b128 v[140:143], v249 offset:16
	v_lshl_add_u64 v[236:237], v[202:203], 2, s[6:7]
	v_lshl_add_u32 v236, v202, 2, v246
	v_mov_b32_e32 v251, 0
	s_andn2_b64 vcc, exec, s[38:39]
	v_lshl_add_u64 v[238:239], v[202:203], 1, s[16:17]
	v_lshl_add_u64 v[238:239], v[204:205], 0, v[238:239]
	s_waitcnt vmcnt(0) lgkmcnt(0)
	v_pk_fma_f32 v[128:129], v[128:129], v[140:141], v[194:195]
	v_cndmask_b32_e64 v194, 0, 1, s[38:39]
	v_pk_fma_f32 v[134:135], v[134:135], v[150:151], v[200:201]
	v_pk_fma_f32 v[132:133], v[132:133], v[148:149], v[198:199]
	v_pk_fma_f32 v[130:131], v[130:131], v[142:143], v[196:197]
	v_cmp_ne_u32_e64 s[46:47], 1, v194
	ds_write_b128 v208, v[132:135]
	ds_write_b128 v208, v[128:131] offset:16
	ds_read_b128 v[216:219], v210
	ds_read_b128 v[220:223], v210 offset:1152
	s_cbranch_vccnz .Lxn_pf_8564
	v_mov_b32_e32 v196, v133
	v_mov_b32_e32 v197, v129
	v_mov_b32_e32 v194, v132
	v_mov_b32_e32 v195, v128
	v_pk_mul_f32 v[196:197], v[196:197], v[196:197]
	v_mov_b32_e32 v198, v135
	v_mov_b32_e32 v199, v131
	v_pk_fma_f32 v[194:195], v[194:195], v[194:195], v[196:197]
	v_mov_b32_e32 v196, v134
	v_mov_b32_e32 v197, v130
	v_pk_mul_f32 v[198:199], v[198:199], v[198:199]
	s_nop 0
	v_pk_fma_f32 v[196:197], v[196:197], v[196:197], v[198:199]
	s_nop 0
	v_pk_add_f32 v[194:195], v[194:195], v[196:197]
	s_nop 0
	v_add_f32_e32 v251, v194, v195
	ds_read_b128 v[194:197], v192
	ds_read_b128 v[198:201], v192 offset:16
	s_waitcnt lgkmcnt(1)
	v_pk_mul_f32 v[134:135], v[134:135], v[196:197]
	v_pk_mul_f32 v[132:133], v[132:133], v[194:195]
	s_waitcnt lgkmcnt(0)
	v_pk_mul_f32 v[194:195], v[130:131], v[200:201]
	v_pk_mul_f32 v[130:131], v[128:129], v[198:199]
	v_cvt_pk_bf16_f32 v128, v132, v133
	v_cvt_pk_bf16_f32 v129, v134, v135
	v_cvt_pk_bf16_f32 v130, v130, v131
	v_cvt_pk_bf16_f32 v131, v194, v195
	ds_bpermute_b32 v128, v206, v128
	ds_bpermute_b32 v129, v206, v129
	ds_bpermute_b32 v130, v206, v130
	ds_bpermute_b32 v131, v206, v131
	s_waitcnt lgkmcnt(0)
	global_store_dwordx4 v[238:239], v[128:131], off
	s_waitcnt lgkmcnt(0)
	global_store_dwordx4 v236, v[216:219], s[6:7]
	global_store_dwordx4 v236, v[220:223], s[100:101]
.LBB0_325:
	ds_read_b128 v[132:135], v249 offset:512
	ds_read_b128 v[128:131], v249 offset:528
	s_lshl_b32 s76, s76, 2
	v_cmp_eq_u32_e64 s[44:45], 0, v250
	s_ashr_i32 s77, s76, 31
	s_waitcnt lgkmcnt(1)
	v_pk_fma_f32 v[126:127], v[126:127], v[134:135], v[190:191]
	v_pk_fma_f32 v[124:125], v[124:125], v[132:133], v[188:189]
	s_waitcnt lgkmcnt(0)
	v_pk_fma_f32 v[122:123], v[122:123], v[130:131], v[186:187]
	v_pk_fma_f32 v[120:121], v[120:121], v[128:129], v[184:185]
	s_and_b64 vcc, exec, s[46:47]
	ds_write_b128 v208, v[124:127]
	ds_write_b128 v208, v[120:123] offset:16
	ds_read_b128 v[216:219], v210
	ds_read_b128 v[220:223], v210 offset:1152
	s_cbranch_vccnz .Lxn_pf_8611
	ds_read_b128 v[184:187], v192 offset:512
	ds_read_b128 v[188:191], v192 offset:528
	s_waitcnt lgkmcnt(1)
	v_pk_mul_f32 v[184:185], v[124:125], v[184:185]
	s_waitcnt lgkmcnt(0)
	v_pk_mul_f32 v[188:189], v[120:121], v[188:189]
	v_mul_f32_e32 v121, v121, v121
	v_mul_f32_e32 v125, v125, v125
	v_fmac_f32_e32 v121, v120, v120
	v_mul_f32_e32 v120, v123, v123
	v_pk_mul_f32 v[190:191], v[122:123], v[190:191]
	v_fmac_f32_e32 v125, v124, v124
	v_mul_f32_e32 v124, v127, v127
	v_fmac_f32_e32 v120, v122, v122
	v_and_b32_e32 v122, 64, v242
	v_fmac_f32_e32 v124, v126, v126
	v_add_f32_e32 v120, v121, v120
	v_xor_b32_e32 v121, 16, v242
	v_add_u32_e32 v122, 64, v122
	v_add_f32_e32 v124, v125, v124
	v_cmp_lt_i32_e32 vcc, v121, v122
	v_add_f32_e32 v120, v124, v120
	v_add_f32_e32 v120, v251, v120
	v_cndmask_b32_e32 v121, v242, v121, vcc
	v_lshlrev_b32_e32 v121, 2, v121
	ds_bpermute_b32 v121, v121, v120
	v_pk_mul_f32 v[186:187], v[126:127], v[186:187]
	v_cvt_pk_bf16_f32 v184, v184, v185
	v_cvt_pk_bf16_f32 v185, v186, v187
	v_cvt_pk_bf16_f32 v186, v188, v189
	s_waitcnt lgkmcnt(0)
	v_add_f32_e32 v120, v120, v121
	v_xor_b32_e32 v121, 32, v242
	v_cmp_lt_i32_e32 vcc, v121, v122
	v_cvt_pk_bf16_f32 v187, v190, v191
	ds_bpermute_b32 v184, v206, v184
	ds_bpermute_b32 v185, v206, v185
	ds_bpermute_b32 v186, v206, v186
	ds_bpermute_b32 v187, v206, v187
	s_waitcnt lgkmcnt(0)
	global_store_dwordx4 v[238:239], v[184:187], off offset:256
	s_waitcnt lgkmcnt(0)
	global_store_dwordx4 v236, v[216:219], s[6:7] offset:512
	global_store_dwordx4 v236, v[220:223], s[100:101] offset:512
	v_cndmask_b32_e32 v121, v242, v121, vcc
	v_lshlrev_b32_e32 v121, 2, v121
	ds_bpermute_b32 v121, v121, v120
	s_and_saveexec_b64 s[54:55], s[44:45]
	s_cbranch_execz .LBB0_328
	v_lshlrev_b64 v[122:123], 6, v[226:227]
	v_lshl_add_u64 v[122:123], s[20:21], 0, v[122:123]
	v_lshl_add_u64 v[122:123], s[76:77], 2, v[122:123]
	s_lshl_b32 s92, s91, 2
	v_lshl_add_u64 v[122:123], v[122:123], 0, s[92:93]
	s_waitcnt lgkmcnt(0)
	v_add_f32_e32 v120, v120, v121
	global_store_dword v[122:123], v120, off

; #define LAS __attribute__((address_space(3)))
; __device__ __forceinline__ unsigned cvt_pk_bf16(float lo, float hi) { const cvt_f32x2_t v = {lo, hi}; const cvt_bf16x2_t b = __builtin_convertvector(v, cvt_bf16x2_t); return __builtin_bit_cast(unsigned, b); }
; __device__ __forceinline__ float sq4(f32x4 v) { return (v[0] * v[0] + v[1] * v[1]) + (v[2] * v[2] + v[3] * v[3]); }
;     __device__ __forceinline__ void operator()(const f32x4 (&acc)[2][2][4][2], const Unit& u, int wr, int wc, int fr, int fq) const {
;     ...
;             for (int m = 0; m < 4; ++m) {
;                 const int row = u.pm * 256 + ai * 128 + wr * 64 + m * 16 + fr;
;                 const size_t off = (size_t)row * DM + col0;
;                 float ss = 0.f;
; #pragma unroll
;                 for (int bj = 0; bj < 2; ++bj) {
;                     const f32x4 xo0 = xr[m][bj][0] + *(const LAS f32x4*)(gtp + 128 * bj) * acc[ai][bj][m][0], xo1 = xr[m][bj][1] + *(const LAS f32x4*)(gtp + 128 * bj + 4) * acc[ai][bj][m][1];
;                     *(f32x4*)(xout + off + 128 * bj) = xo0; *(f32x4*)(xout + off + 128 * bj + 4) = xo1;
;                     if (gmn) { ss += sq4(xo0) + sq4(xo1); const f32x4 a = xo0 * *(const LAS f32x4*)(gmp + 128 * bj), c = xo1 * *(const LAS f32x4*)(gmp + 128 * bj + 4);
;                         u32x4 w; w.x = cvt_pk_bf16(a[0], a[1]); w.y = cvt_pk_bf16(a[2], a[3]); w.z = cvt_pk_bf16(c[0], c[1]); w.w = cvt_pk_bf16(c[2], c[3]); *(u32x4*)(AX + off + 128 * bj) = w; }
;                 }
;                 if (gmn) { ss += __shfl_xor(ss, 16); ss += __shfl_xor(ss, 32); if (fq == 0) statx[(size_t)row * 16 + u.pn * 4 + wc] = ss; }
.LBB0_329:
	s_waitcnt lgkmcnt(0)
	v_lshlrev_b64 v[120:121], 10, v[234:235]
	v_lshl_add_u64 v[184:185], v[120:121], 0, v[224:225]
	v_pk_fma_f32 v[120:121], v[118:119], v[150:151], v[182:183]
	v_pk_fma_f32 v[118:119], v[116:117], v[148:149], v[180:181]
	v_pk_fma_f32 v[124:125], v[110:111], v[142:143], v[178:179]
	v_pk_fma_f32 v[122:123], v[108:109], v[140:141], v[176:177]
	v_lshl_add_u64 v[126:127], v[184:185], 2, s[6:7]
	v_lshl_add_u32 v126, v184, 2, v246
	s_mov_b64 s[54:55], -1
	s_and_b64 vcc, exec, s[46:47]
	v_pk_fma_f32 v[116:117], v[100:101], v[132:133], v[172:173]
	v_pk_fma_f32 v[108:109], v[92:93], v[128:129], v[168:169]
	ds_write_b128 v208, v[118:121]
	ds_write_b128 v208, v[122:125] offset:16
	ds_read_b128 v[216:219], v210
	ds_read_b128 v[220:223], v210 offset:1152
	s_cbranch_vccnz .Lxn_pf_8680
	v_mul_f32_e32 v92, v119, v119
	v_mul_f32_e32 v93, v121, v121
	ds_read_b128 v[176:179], v192
	ds_read_b128 v[180:183], v192 offset:16
	v_fmac_f32_e32 v92, v118, v118
	v_fmac_f32_e32 v93, v120, v120
	v_add_f32_e32 v92, v92, v93
	v_mul_f32_e32 v93, v123, v123
	v_mul_f32_e32 v100, v125, v125
	v_fmac_f32_e32 v93, v122, v122
	v_fmac_f32_e32 v100, v124, v124
	v_add_f32_e32 v93, v93, v100
	v_add_f32_e32 v172, v92, v93
	s_waitcnt lgkmcnt(1)
	v_pk_mul_f32 v[92:93], v[120:121], v[178:179]
	v_pk_mul_f32 v[100:101], v[118:119], v[176:177]
	s_waitcnt lgkmcnt(0)
	v_pk_mul_f32 v[110:111], v[124:125], v[182:183]
	v_pk_mul_f32 v[120:121], v[122:123], v[180:181]
	v_cvt_pk_bf16_f32 v118, v100, v101
	v_cvt_pk_bf16_f32 v119, v92, v93
	v_cvt_pk_bf16_f32 v120, v120, v121
	v_cvt_pk_bf16_f32 v121, v110, v111
	v_lshl_add_u64 v[92:93], v[184:185], 1, s[16:17]
	ds_bpermute_b32 v118, v206, v118
	ds_bpermute_b32 v119, v206, v119
	ds_bpermute_b32 v120, v206, v120
	ds_bpermute_b32 v121, v206, v121
	s_waitcnt lgkmcnt(0)
	v_lshl_add_u64 v[92:93], v[204:205], 0, v[92:93]
	global_store_dwordx4 v[92:93], v[118:121], off
	s_waitcnt lgkmcnt(0)
	global_store_dwordx4 v126, v[216:219], s[6:7]
	global_store_dwordx4 v126, v[220:223], s[100:101]
	v_pk_fma_f32 v[110:111], v[94:95], v[130:131], v[170:171]
	s_nop 0
	v_pk_fma_f32 v[118:119], v[102:103], v[134:135], v[174:175]
	ds_write_b128 v208, v[116:119]
	ds_write_b128 v208, v[108:111] offset:16
	ds_read_b128 v[216:219], v210
	ds_read_b128 v[220:223], v210 offset:1152
	ds_read_b128 v[120:123], v192 offset:512
	s_waitcnt lgkmcnt(0)
	v_pk_mul_f32 v[100:101], v[118:119], v[122:123]
	v_pk_mul_f32 v[124:125], v[116:117], v[120:121]
	ds_read_b128 v[120:123], v192 offset:528
	s_waitcnt lgkmcnt(0)
	v_pk_mul_f32 v[168:169], v[110:111], v[122:123]
	v_pk_mul_f32 v[122:123], v[108:109], v[120:121]
	v_cvt_pk_bf16_f32 v120, v124, v125
	v_cvt_pk_bf16_f32 v121, v100, v101
	v_cvt_pk_bf16_f32 v122, v122, v123
	v_cvt_pk_bf16_f32 v123, v168, v169
	ds_bpermute_b32 v120, v206, v120
	ds_bpermute_b32 v121, v206, v121
	ds_bpermute_b32 v122, v206, v122
	ds_bpermute_b32 v123, v206, v123
	s_waitcnt lgkmcnt(0)
	global_store_dwordx4 v[92:93], v[120:123], off offset:256
	s_waitcnt lgkmcnt(0)
	global_store_dwordx4 v126, v[216:219], s[6:7] offset:512
	global_store_dwordx4 v126, v[220:223], s[100:101] offset:512
	v_mul_f32_e32 v92, v117, v117
	v_mul_f32_e32 v93, v119, v119
	v_fmac_f32_e32 v92, v116, v116
	v_fmac_f32_e32 v93, v118, v118
	v_add_f32_e32 v92, v92, v93
	v_mul_f32_e32 v93, v109, v109
	v_mul_f32_e32 v100, v111, v111
	v_fmac_f32_e32 v93, v108, v108
	v_fmac_f32_e32 v100, v110, v110
	v_add_f32_e32 v93, v93, v100
	v_and_b32_e32 v100, 64, v242
	v_add_f32_e32 v92, v92, v93
	v_xor_b32_e32 v93, 16, v242
	v_add_u32_e32 v100, 64, v100
	v_cmp_lt_i32_e32 vcc, v93, v100
	v_add_f32_e32 v92, v172, v92
	s_nop 0
	v_cndmask_b32_e32 v93, v242, v93, vcc
	v_lshlrev_b32_e32 v93, 2, v93
	ds_bpermute_b32 v93, v93, v92
	s_waitcnt lgkmcnt(0)
	v_add_f32_e32 v92, v92, v93
	v_xor_b32_e32 v93, 32, v242
	v_cmp_lt_i32_e32 vcc, v93, v100
	s_nop 1
	v_cndmask_b32_e32 v93, v242, v93, vcc
	v_lshlrev_b32_e32 v93, 2, v93
	ds_bpermute_b32 v93, v93, v92
	s_and_saveexec_b64 s[54:55], s[44:45]
	s_cbranch_execz .LBB0_332
	v_lshlrev_b64 v[100:101], 6, v[234:235]
	v_lshl_add_u64 v[100:101], s[20:21], 0, v[100:101]
	v_lshl_add_u64 v[100:101], s[76:77], 2, v[100:101]
	s_lshl_b32 s92, s91, 2
	v_lshl_add_u64 v[100:101], v[100:101], 0, s[92:93]
	s_waitcnt lgkmcnt(0)
	v_add_f32_e32 v92, v92, v93
	global_store_dword v[100:101], v92, off

; #define LAS __attribute__((address_space(3)))
; __device__ __forceinline__ unsigned cvt_pk_bf16(float lo, float hi) { const cvt_f32x2_t v = {lo, hi}; const cvt_bf16x2_t b = __builtin_convertvector(v, cvt_bf16x2_t); return __builtin_bit_cast(unsigned, b); }
; __device__ __forceinline__ float sq4(f32x4 v) { return (v[0] * v[0] + v[1] * v[1]) + (v[2] * v[2] + v[3] * v[3]); }
;     __device__ __forceinline__ void operator()(const f32x4 (&acc)[2][2][4][2], const Unit& u, int wr, int wc, int fr, int fq) const {
;     ...
;             for (int m = 0; m < 4; ++m) {
;                 const int row = u.pm * 256 + ai * 128 + wr * 64 + m * 16 + fr;
;                 const size_t off = (size_t)row * DM + col0;
;                 float ss = 0.f;
; #pragma unroll
;                 for (int bj = 0; bj < 2; ++bj) {
;                     const f32x4 xo0 = xr[m][bj][0] + *(const LAS f32x4*)(gtp + 128 * bj) * acc[ai][bj][m][0], xo1 = xr[m][bj][1] + *(const LAS f32x4*)(gtp + 128 * bj + 4) * acc[ai][bj][m][1];
;                     *(f32x4*)(xout + off + 128 * bj) = xo0; *(f32x4*)(xout + off + 128 * bj + 4) = xo1;
;                     if (gmn) { ss += sq4(xo0) + sq4(xo1); const f32x4 a = xo0 * *(const LAS f32x4*)(gmp + 128 * bj), c = xo1 * *(const LAS f32x4*)(gmp + 128 * bj + 4);
;                         u32x4 w; w.x = cvt_pk_bf16(a[0], a[1]); w.y = cvt_pk_bf16(a[2], a[3]); w.z = cvt_pk_bf16(c[0], c[1]); w.w = cvt_pk_bf16(c[2], c[3]); *(u32x4*)(AX + off + 128 * bj) = w; }
;                 }
;                 if (gmn) { ss += __shfl_xor(ss, 16); ss += __shfl_xor(ss, 32); if (fq == 0) statx[(size_t)row * 16 + u.pn * 4 + wc] = ss; }
.LBB0_335:
	s_waitcnt lgkmcnt(0)
	v_lshlrev_b64 v[92:93], 10, v[232:233]
	v_lshl_add_u64 v[94:95], v[92:93], 0, v[224:225]
	v_pk_fma_f32 v[98:99], v[98:99], v[150:151], v[166:167]
	v_pk_fma_f32 v[96:97], v[96:97], v[148:149], v[164:165]
	v_pk_fma_f32 v[102:103], v[90:91], v[142:143], v[162:163]
	v_pk_fma_f32 v[100:101], v[88:89], v[140:141], v[160:161]
	v_lshl_add_u64 v[108:109], v[94:95], 2, s[6:7]
	v_lshl_add_u32 v108, v94, 2, v246
	s_mov_b64 s[54:55], -1
	s_and_b64 vcc, exec, s[46:47]
	v_pk_fma_f32 v[92:93], v[84:85], v[132:133], v[156:157]
	v_pk_fma_f32 v[88:89], v[76:77], v[128:129], v[152:153]
	ds_write_b128 v208, v[96:99]
	ds_write_b128 v208, v[100:103] offset:16
	ds_read_b128 v[216:219], v210
	ds_read_b128 v[220:223], v210 offset:1152
	s_cbranch_vccnz .Lxn_pf_8790
	v_mul_f32_e32 v76, v97, v97
	v_mul_f32_e32 v77, v99, v99
	ds_read_b128 v[116:119], v192
	ds_read_b128 v[120:123], v192 offset:16
	v_fmac_f32_e32 v76, v96, v96
	v_fmac_f32_e32 v77, v98, v98
	v_add_f32_e32 v76, v76, v77
	v_mul_f32_e32 v77, v101, v101
	v_mul_f32_e32 v84, v103, v103
	v_fmac_f32_e32 v77, v100, v100
	v_fmac_f32_e32 v84, v102, v102
	v_add_f32_e32 v77, v77, v84
	v_add_f32_e32 v110, v76, v77
	s_waitcnt lgkmcnt(1)
	v_pk_mul_f32 v[76:77], v[98:99], v[118:119]
	v_pk_mul_f32 v[84:85], v[96:97], v[116:117]
	s_waitcnt lgkmcnt(0)
	v_pk_mul_f32 v[90:91], v[102:103], v[122:123]
	v_pk_mul_f32 v[98:99], v[100:101], v[120:121]
	v_cvt_pk_bf16_f32 v96, v84, v85
	v_cvt_pk_bf16_f32 v97, v76, v77
	v_cvt_pk_bf16_f32 v98, v98, v99
	v_cvt_pk_bf16_f32 v99, v90, v91
	v_lshl_add_u64 v[76:77], v[94:95], 1, s[16:17]
	v_lshl_add_u64 v[76:77], v[204:205], 0, v[76:77]
	v_pk_fma_f32 v[94:95], v[86:87], v[134:135], v[158:159]
	ds_bpermute_b32 v96, v206, v96
	ds_bpermute_b32 v97, v206, v97
	ds_bpermute_b32 v98, v206, v98
	ds_bpermute_b32 v99, v206, v99
	s_waitcnt lgkmcnt(0)
	global_store_dwordx4 v[76:77], v[96:99], off
	s_waitcnt lgkmcnt(0)
	global_store_dwordx4 v108, v[216:219], s[6:7]
	global_store_dwordx4 v108, v[220:223], s[100:101]
	v_pk_fma_f32 v[90:91], v[78:79], v[130:131], v[154:155]
	ds_write_b128 v208, v[92:95]
	ds_write_b128 v208, v[88:91] offset:16
	ds_read_b128 v[216:219], v210
	ds_read_b128 v[220:223], v210 offset:1152
	ds_read_b128 v[96:99], v192 offset:512
	s_waitcnt lgkmcnt(0)
	v_pk_mul_f32 v[84:85], v[94:95], v[98:99]
	v_pk_mul_f32 v[100:101], v[92:93], v[96:97]
	ds_read_b128 v[96:99], v192 offset:528
	s_waitcnt lgkmcnt(0)
	v_pk_mul_f32 v[102:103], v[90:91], v[98:99]
	v_pk_mul_f32 v[98:99], v[88:89], v[96:97]
	v_cvt_pk_bf16_f32 v96, v100, v101
	v_cvt_pk_bf16_f32 v97, v84, v85
	v_cvt_pk_bf16_f32 v98, v98, v99
	v_cvt_pk_bf16_f32 v99, v102, v103
	ds_bpermute_b32 v96, v206, v96
	ds_bpermute_b32 v97, v206, v97
	ds_bpermute_b32 v98, v206, v98
	ds_bpermute_b32 v99, v206, v99
	s_waitcnt lgkmcnt(0)
	global_store_dwordx4 v[76:77], v[96:99], off offset:256
	s_waitcnt lgkmcnt(0)
	global_store_dwordx4 v108, v[216:219], s[6:7] offset:512
	global_store_dwordx4 v108, v[220:223], s[100:101] offset:512
	v_mul_f32_e32 v76, v93, v93
	v_mul_f32_e32 v77, v95, v95
	v_fmac_f32_e32 v76, v92, v92
	v_fmac_f32_e32 v77, v94, v94
	v_add_f32_e32 v76, v76, v77
	v_mul_f32_e32 v77, v89, v89
	v_mul_f32_e32 v84, v91, v91
	v_fmac_f32_e32 v77, v88, v88
	v_fmac_f32_e32 v84, v90, v90
	v_add_f32_e32 v77, v77, v84
	v_and_b32_e32 v84, 64, v242
	v_add_f32_e32 v76, v76, v77
	v_xor_b32_e32 v77, 16, v242
	v_add_u32_e32 v84, 64, v84
	v_cmp_lt_i32_e32 vcc, v77, v84
	v_add_f32_e32 v76, v110, v76
	s_nop 0
	v_cndmask_b32_e32 v77, v242, v77, vcc
	v_lshlrev_b32_e32 v77, 2, v77
	ds_bpermute_b32 v77, v77, v76
	s_waitcnt lgkmcnt(0)
	v_add_f32_e32 v76, v76, v77
	v_xor_b32_e32 v77, 32, v242
	v_cmp_lt_i32_e32 vcc, v77, v84
	s_nop 1
	v_cndmask_b32_e32 v77, v242, v77, vcc
	v_lshlrev_b32_e32 v77, 2, v77
	ds_bpermute_b32 v77, v77, v76
	s_and_saveexec_b64 s[54:55], s[44:45]
	s_cbranch_execz .LBB0_338
	v_lshlrev_b64 v[84:85], 6, v[232:233]
	v_lshl_add_u64 v[84:85], s[20:21], 0, v[84:85]
	v_lshl_add_u64 v[84:85], s[76:77], 2, v[84:85]
	s_lshl_b32 s92, s91, 2
	v_lshl_add_u64 v[84:85], v[84:85], 0, s[92:93]
	s_waitcnt lgkmcnt(0)
	v_add_f32_e32 v76, v76, v77
	global_store_dword v[84:85], v76, off

; #define LAS __attribute__((address_space(3)))
; __device__ __forceinline__ unsigned cvt_pk_bf16(float lo, float hi) { const cvt_f32x2_t v = {lo, hi}; const cvt_bf16x2_t b = __builtin_convertvector(v, cvt_bf16x2_t); return __builtin_bit_cast(unsigned, b); }
; __device__ __forceinline__ float sq4(f32x4 v) { return (v[0] * v[0] + v[1] * v[1]) + (v[2] * v[2] + v[3] * v[3]); }
;     __device__ __forceinline__ void operator()(const f32x4 (&acc)[2][2][4][2], const Unit& u, int wr, int wc, int fr, int fq) const {
;     ...
;             for (int m = 0; m < 4; ++m) {
;                 const int row = u.pm * 256 + ai * 128 + wr * 64 + m * 16 + fr;
;                 const size_t off = (size_t)row * DM + col0;
;                 float ss = 0.f;
; #pragma unroll
;                 for (int bj = 0; bj < 2; ++bj) {
;                     const f32x4 xo0 = xr[m][bj][0] + *(const LAS f32x4*)(gtp + 128 * bj) * acc[ai][bj][m][0], xo1 = xr[m][bj][1] + *(const LAS f32x4*)(gtp + 128 * bj + 4) * acc[ai][bj][m][1];
;                     *(f32x4*)(xout + off + 128 * bj) = xo0; *(f32x4*)(xout + off + 128 * bj + 4) = xo1;
;                     if (gmn) { ss += sq4(xo0) + sq4(xo1); const f32x4 a = xo0 * *(const LAS f32x4*)(gmp + 128 * bj), c = xo1 * *(const LAS f32x4*)(gmp + 128 * bj + 4);
;                         u32x4 w; w.x = cvt_pk_bf16(a[0], a[1]); w.y = cvt_pk_bf16(a[2], a[3]); w.z = cvt_pk_bf16(c[0], c[1]); w.w = cvt_pk_bf16(c[2], c[3]); *(u32x4*)(AX + off + 128 * bj) = w; }
;                 }
;                 if (gmn) { ss += __shfl_xor(ss, 16); ss += __shfl_xor(ss, 32); if (fq == 0) statx[(size_t)row * 16 + u.pn * 4 + wc] = ss; }
.LBB0_341:
	s_waitcnt lgkmcnt(0)
	v_lshlrev_b64 v[76:77], 10, v[230:231]
	v_lshl_add_u64 v[78:79], v[76:77], 0, v[224:225]
	v_pk_fma_f32 v[82:83], v[82:83], v[150:151], v[146:147]
	v_pk_fma_f32 v[80:81], v[80:81], v[148:149], v[144:145]
	v_pk_fma_f32 v[86:87], v[74:75], v[142:143], v[138:139]
	v_pk_fma_f32 v[84:85], v[72:73], v[140:141], v[136:137]
	v_lshl_add_u64 v[88:89], v[78:79], 2, s[6:7]
	v_lshl_add_u32 v88, v78, 2, v246
	s_mov_b64 s[54:55], -1
	s_and_b64 vcc, exec, s[46:47]
	v_pk_fma_f32 v[76:77], v[68:69], v[132:133], v[112:113]
	v_pk_fma_f32 v[72:73], v[64:65], v[128:129], v[104:105]
	ds_write_b128 v208, v[80:83]
	ds_write_b128 v208, v[84:87] offset:16
	ds_read_b128 v[216:219], v210
	ds_read_b128 v[220:223], v210 offset:1152
	s_cbranch_vccnz .Lxn_pf_8899
	v_mul_f32_e32 v64, v81, v81
	v_mul_f32_e32 v65, v83, v83
	ds_read_b128 v[90:93], v192
	ds_read_b128 v[94:97], v192 offset:16
	v_fmac_f32_e32 v64, v80, v80
	v_fmac_f32_e32 v65, v82, v82
	v_add_f32_e32 v64, v64, v65
	v_mul_f32_e32 v65, v85, v85
	v_mul_f32_e32 v68, v87, v87
	v_fmac_f32_e32 v65, v84, v84
	v_fmac_f32_e32 v68, v86, v86
	v_add_f32_e32 v65, v65, v68
	v_add_f32_e32 v98, v64, v65
	s_waitcnt lgkmcnt(1)
	v_pk_mul_f32 v[64:65], v[82:83], v[92:93]
	v_pk_mul_f32 v[68:69], v[80:81], v[90:91]
	s_waitcnt lgkmcnt(0)
	v_pk_mul_f32 v[74:75], v[86:87], v[96:97]
	v_pk_mul_f32 v[82:83], v[84:85], v[94:95]
	v_cvt_pk_bf16_f32 v80, v68, v69
	v_cvt_pk_bf16_f32 v81, v64, v65
	v_cvt_pk_bf16_f32 v82, v82, v83
	v_cvt_pk_bf16_f32 v83, v74, v75
	v_lshl_add_u64 v[64:65], v[78:79], 1, s[16:17]
	v_lshl_add_u64 v[64:65], v[204:205], 0, v[64:65]
	v_pk_fma_f32 v[78:79], v[70:71], v[134:135], v[114:115]
	ds_bpermute_b32 v80, v206, v80
	ds_bpermute_b32 v81, v206, v81
	ds_bpermute_b32 v82, v206, v82
	ds_bpermute_b32 v83, v206, v83
	s_waitcnt lgkmcnt(0)
	global_store_dwordx4 v[64:65], v[80:83], off
	s_waitcnt lgkmcnt(0)
	global_store_dwordx4 v88, v[216:219], s[6:7]
	global_store_dwordx4 v88, v[220:223], s[100:101]
	v_pk_fma_f32 v[74:75], v[66:67], v[130:131], v[106:107]
	ds_write_b128 v208, v[76:79]
	ds_write_b128 v208, v[72:75] offset:16
	ds_read_b128 v[216:219], v210
	ds_read_b128 v[220:223], v210 offset:1152
	ds_read_b128 v[80:83], v192 offset:512
	s_waitcnt lgkmcnt(0)
	v_pk_mul_f32 v[68:69], v[78:79], v[82:83]
	v_pk_mul_f32 v[84:85], v[76:77], v[80:81]
	ds_read_b128 v[80:83], v192 offset:528
	s_waitcnt lgkmcnt(0)
	v_pk_mul_f32 v[86:87], v[74:75], v[82:83]
	v_pk_mul_f32 v[82:83], v[72:73], v[80:81]
	v_cvt_pk_bf16_f32 v80, v84, v85
	v_cvt_pk_bf16_f32 v81, v68, v69
	v_cvt_pk_bf16_f32 v82, v82, v83
	v_cvt_pk_bf16_f32 v83, v86, v87
	ds_bpermute_b32 v80, v206, v80
	ds_bpermute_b32 v81, v206, v81
	ds_bpermute_b32 v82, v206, v82
	ds_bpermute_b32 v83, v206, v83
	s_waitcnt lgkmcnt(0)
	global_store_dwordx4 v[64:65], v[80:83], off offset:256
	s_waitcnt lgkmcnt(0)
	global_store_dwordx4 v88, v[216:219], s[6:7] offset:512
	global_store_dwordx4 v88, v[220:223], s[100:101] offset:512
	v_mul_f32_e32 v64, v77, v77
	v_mul_f32_e32 v65, v79, v79
	v_fmac_f32_e32 v64, v76, v76
	v_fmac_f32_e32 v65, v78, v78
	v_add_f32_e32 v64, v64, v65
	v_mul_f32_e32 v65, v73, v73
	v_mul_f32_e32 v68, v75, v75
	v_fmac_f32_e32 v65, v72, v72
	v_fmac_f32_e32 v68, v74, v74
	v_add_f32_e32 v65, v65, v68
	v_and_b32_e32 v68, 64, v242
	v_add_f32_e32 v64, v64, v65
	v_xor_b32_e32 v65, 16, v242
	v_add_u32_e32 v68, 64, v68
	v_cmp_lt_i32_e32 vcc, v65, v68
	v_add_f32_e32 v64, v98, v64
	s_nop 0
	v_cndmask_b32_e32 v65, v242, v65, vcc
	v_lshlrev_b32_e32 v65, 2, v65
	ds_bpermute_b32 v65, v65, v64
	s_waitcnt lgkmcnt(0)
	v_add_f32_e32 v64, v64, v65
	v_xor_b32_e32 v65, 32, v242
	v_cmp_lt_i32_e32 vcc, v65, v68
	s_nop 1
	v_cndmask_b32_e32 v65, v242, v65, vcc
	v_lshlrev_b32_e32 v65, 2, v65
	ds_bpermute_b32 v65, v65, v64
	s_and_saveexec_b64 s[54:55], s[44:45]
	s_cbranch_execz .LBB0_344
	v_lshlrev_b64 v[68:69], 6, v[230:231]
	v_lshl_add_u64 v[68:69], s[20:21], 0, v[68:69]
	v_lshl_add_u64 v[68:69], s[76:77], 2, v[68:69]
	s_lshl_b32 s92, s91, 2
	v_lshl_add_u64 v[68:69], v[68:69], 0, s[92:93]
	s_waitcnt lgkmcnt(0)
	v_add_f32_e32 v64, v64, v65
	global_store_dword v[68:69], v64, off

; #define LAS __attribute__((address_space(3)))
; __device__ __forceinline__ unsigned cvt_pk_bf16(float lo, float hi) { const cvt_f32x2_t v = {lo, hi}; const cvt_bf16x2_t b = __builtin_convertvector(v, cvt_bf16x2_t); return __builtin_bit_cast(unsigned, b); }
; __device__ __forceinline__ float sq4(f32x4 v) { return (v[0] * v[0] + v[1] * v[1]) + (v[2] * v[2] + v[3] * v[3]); }
;     __device__ __forceinline__ void operator()(const f32x4 (&acc)[2][2][4][2], const Unit& u, int wr, int wc, int fr, int fq) const {
;     ...
;             for (int m = 0; m < 4; ++m) { const size_t off = (size_t)(u.pm * 256 + ai * 128 + wr * 64 + m * 16 + fr) * DM + col0;
; #pragma unroll
;                 for (int bj = 0; bj < 2; ++bj)
; #pragma unroll
;                     for (int n = 0; n < 2; ++n) xr[m][bj][n] = *(const f32x4*)(xin + off + 128 * bj + 4 * n); }
;             asm volatile("" ::: "memory");
; #pragma unroll
;             for (int m = 0; m < 4; ++m) {
;                 const int row = u.pm * 256 + ai * 128 + wr * 64 + m * 16 + fr;
;                 const size_t off = (size_t)row * DM + col0;
;                 float ss = 0.f;
; #pragma unroll
;                 for (int bj = 0; bj < 2; ++bj) {
;                     const f32x4 xo0 = xr[m][bj][0] + *(const LAS f32x4*)(gtp + 128 * bj) * acc[ai][bj][m][0], xo1 = xr[m][bj][1] + *(const LAS f32x4*)(gtp + 128 * bj + 4) * acc[ai][bj][m][1];
;                     *(f32x4*)(xout + off + 128 * bj) = xo0; *(f32x4*)(xout + off + 128 * bj + 4) = xo1;
;                     if (gmn) { ss += sq4(xo0) + sq4(xo1); const f32x4 a = xo0 * *(const LAS f32x4*)(gmp + 128 * bj), c = xo1 * *(const LAS f32x4*)(gmp + 128 * bj + 4);
;                         u32x4 w; w.x = cvt_pk_bf16(a[0], a[1]); w.y = cvt_pk_bf16(a[2], a[3]); w.z = cvt_pk_bf16(c[0], c[1]); w.w = cvt_pk_bf16(c[2], c[3]); *(u32x4*)(AX + off + 128 * bj) = w; }
;                 }
;                 if (gmn) { ss += __shfl_xor(ss, 16); ss += __shfl_xor(ss, 32); if (fq == 0) statx[(size_t)row * 16 + u.pn * 4 + wc] = ss; }
.LBB0_347:
	v_add_u32_e32 v134, 0x80, v226
	v_ashrrev_i32_e32 v135, 31, v134
	s_waitcnt lgkmcnt(0)
	v_lshlrev_b64 v[64:65], 12, v[134:135]
	v_add_u32_e32 v132, 0x90, v226
	v_lshl_add_u64 v[64:65], v[228:229], 0, v[64:65]
	v_ashrrev_i32_e32 v133, 31, v132
	global_load_dwordx4 v[136:139], v[64:65], off offset:16
	global_load_dwordx4 v[140:143], v[64:65], off
	global_load_dwordx4 v[120:123], v[64:65], off offset:528
	global_load_dwordx4 v[124:127], v[64:65], off offset:512
	v_lshlrev_b64 v[64:65], 12, v[132:133]
	v_add_u32_e32 v130, 0xa0, v226
	v_lshl_add_u64 v[64:65], v[228:229], 0, v[64:65]
	v_ashrrev_i32_e32 v131, 31, v130
	global_load_dwordx4 v[112:115], v[64:65], off offset:16
	global_load_dwordx4 v[116:119], v[64:65], off
	global_load_dwordx4 v[104:107], v[64:65], off offset:528
	global_load_dwordx4 v[108:111], v[64:65], off offset:512
	v_lshlrev_b64 v[64:65], 12, v[130:131]
	v_add_u32_e32 v128, 0xb0, v226
	v_lshl_add_u64 v[64:65], v[228:229], 0, v[64:65]
	v_ashrrev_i32_e32 v129, 31, v128
	global_load_dwordx4 v[96:99], v[64:65], off offset:16
	global_load_dwordx4 v[100:103], v[64:65], off
	global_load_dwordx4 v[88:91], v[64:65], off offset:528
	global_load_dwordx4 v[92:95], v[64:65], off offset:512
	v_lshlrev_b64 v[64:65], 12, v[128:129]
	v_lshl_add_u64 v[68:69], v[228:229], 0, v[64:65]
	global_load_dwordx4 v[72:75], v[68:69], off offset:16
	global_load_dwordx4 v[80:83], v[68:69], off
	global_load_dwordx4 v[64:67], v[68:69], off offset:528
	s_nop 0
	global_load_dwordx4 v[68:71], v[68:69], off offset:512
	v_lshlrev_b64 v[76:77], 10, v[134:135]
	v_lshl_add_u64 v[144:145], v[76:77], 0, v[224:225]
	ds_read_b128 v[84:87], v249
	ds_read_b128 v[76:79], v249 offset:16
	s_and_b64 vcc, exec, s[46:47]
	s_waitcnt vmcnt(15) lgkmcnt(0)
	v_pk_fma_f32 v[58:59], v[58:59], v[78:79], v[138:139]
	s_waitcnt vmcnt(14)
	v_pk_fma_f32 v[62:63], v[62:63], v[86:87], v[142:143]
	v_pk_fma_f32 v[60:61], v[60:61], v[84:85], v[140:141]
	v_pk_fma_f32 v[56:57], v[56:57], v[76:77], v[136:137]
	v_lshl_add_u64 v[136:137], v[144:145], 2, s[6:7]
	v_lshl_add_u32 v136, v144, 2, v246
	v_mov_b32_e32 v140, 0
	v_lshl_add_u64 v[138:139], v[144:145], 1, s[16:17]
	v_lshl_add_u64 v[138:139], v[204:205], 0, v[138:139]
	ds_write_b128 v208, v[60:63]
	ds_write_b128 v208, v[56:59] offset:16
	ds_read_b128 v[216:219], v210
	ds_read_b128 v[220:223], v210 offset:1152
	s_cbranch_vccnz .Lxn_pf_9046
	v_mov_b32_e32 v142, v61
	v_mov_b32_e32 v143, v57
	v_mov_b32_e32 v140, v60
	v_mov_b32_e32 v141, v56
	v_pk_mul_f32 v[142:143], v[142:143], v[142:143]
	v_mov_b32_e32 v144, v63
	v_mov_b32_e32 v145, v59
	v_pk_fma_f32 v[140:141], v[140:141], v[140:141], v[142:143]
	v_mov_b32_e32 v142, v62
	v_mov_b32_e32 v143, v58
	v_pk_mul_f32 v[144:145], v[144:145], v[144:145]
	s_nop 0
	v_pk_fma_f32 v[142:143], v[142:143], v[142:143], v[144:145]
	s_nop 0
	v_pk_add_f32 v[140:141], v[140:141], v[142:143]
	ds_read_b128 v[142:145], v192
	ds_read_b128 v[146:149], v192 offset:16
	v_add_f32_e32 v140, v140, v141
	s_waitcnt lgkmcnt(1)
	v_pk_mul_f32 v[62:63], v[62:63], v[144:145]
	v_pk_mul_f32 v[60:61], v[60:61], v[142:143]
	s_waitcnt lgkmcnt(0)
	v_pk_mul_f32 v[142:143], v[58:59], v[148:149]
	v_pk_mul_f32 v[58:59], v[56:57], v[146:147]
	v_cvt_pk_bf16_f32 v56, v60, v61
	v_cvt_pk_bf16_f32 v57, v62, v63
	v_cvt_pk_bf16_f32 v58, v58, v59
	v_cvt_pk_bf16_f32 v59, v142, v143
	ds_bpermute_b32 v56, v206, v56
	ds_bpermute_b32 v57, v206, v57
	ds_bpermute_b32 v58, v206, v58
	ds_bpermute_b32 v59, v206, v59
	s_waitcnt lgkmcnt(0)
	global_store_dwordx4 v[138:139], v[56:59], off
	s_waitcnt lgkmcnt(0)
	global_store_dwordx4 v136, v[216:219], s[6:7]
	global_store_dwordx4 v136, v[220:223], s[100:101]
.LBB0_349:
	ds_read_b128 v[60:63], v249 offset:512
	ds_read_b128 v[56:59], v249 offset:528
	s_and_b64 vcc, exec, s[46:47]
	s_waitcnt vmcnt(14) lgkmcnt(1)
	v_pk_fma_f32 v[54:55], v[54:55], v[62:63], v[126:127]
	v_pk_fma_f32 v[52:53], v[52:53], v[60:61], v[124:125]
	s_waitcnt lgkmcnt(0)
	v_pk_fma_f32 v[50:51], v[50:51], v[58:59], v[122:123]
	v_pk_fma_f32 v[48:49], v[48:49], v[56:57], v[120:121]
	ds_write_b128 v208, v[52:55]
	ds_write_b128 v208, v[48:51] offset:16
	ds_read_b128 v[216:219], v210
	ds_read_b128 v[220:223], v210 offset:1152
	s_cbranch_vccnz .Lxn_pf_9089
	ds_read_b128 v[120:123], v192 offset:512
	ds_read_b128 v[124:127], v192 offset:528
	s_waitcnt lgkmcnt(1)
	v_pk_mul_f32 v[120:121], v[52:53], v[120:121]
	s_waitcnt lgkmcnt(0)
	v_pk_mul_f32 v[124:125], v[48:49], v[124:125]
	v_mul_f32_e32 v49, v49, v49
	v_mul_f32_e32 v53, v53, v53
	v_fmac_f32_e32 v49, v48, v48
	v_mul_f32_e32 v48, v51, v51
	v_pk_mul_f32 v[126:127], v[50:51], v[126:127]
	v_fmac_f32_e32 v53, v52, v52
	v_mul_f32_e32 v52, v55, v55
	v_fmac_f32_e32 v48, v50, v50
	v_and_b32_e32 v50, 64, v242
	v_fmac_f32_e32 v52, v54, v54
	v_add_f32_e32 v48, v49, v48
	v_xor_b32_e32 v49, 16, v242
	v_add_u32_e32 v50, 64, v50
	v_add_f32_e32 v52, v53, v52
	v_cmp_lt_i32_e32 vcc, v49, v50
	v_add_f32_e32 v48, v52, v48
	v_add_f32_e32 v48, v140, v48
	v_cndmask_b32_e32 v49, v242, v49, vcc
	v_lshlrev_b32_e32 v49, 2, v49
	ds_bpermute_b32 v49, v49, v48
	v_pk_mul_f32 v[122:123], v[54:55], v[122:123]
	v_cvt_pk_bf16_f32 v120, v120, v121
	v_cvt_pk_bf16_f32 v121, v122, v123
	v_cvt_pk_bf16_f32 v122, v124, v125
	s_waitcnt lgkmcnt(0)
	v_add_f32_e32 v48, v48, v49
	v_xor_b32_e32 v49, 32, v242
	v_cmp_lt_i32_e32 vcc, v49, v50
	v_cvt_pk_bf16_f32 v123, v126, v127
	ds_bpermute_b32 v120, v206, v120
	ds_bpermute_b32 v121, v206, v121
	ds_bpermute_b32 v122, v206, v122
	ds_bpermute_b32 v123, v206, v123
	s_waitcnt lgkmcnt(0)
	global_store_dwordx4 v[138:139], v[120:123], off offset:256
	s_waitcnt lgkmcnt(0)
	global_store_dwordx4 v136, v[216:219], s[6:7] offset:512
	global_store_dwordx4 v136, v[220:223], s[100:101] offset:512
	v_cndmask_b32_e32 v49, v242, v49, vcc
	v_lshlrev_b32_e32 v49, 2, v49
	ds_bpermute_b32 v49, v49, v48
	s_and_saveexec_b64 s[54:55], s[44:45]
	s_cbranch_execz .LBB0_352
	v_lshlrev_b64 v[50:51], 6, v[134:135]
	v_lshl_add_u64 v[50:51], s[20:21], 0, v[50:51]
	v_lshl_add_u64 v[50:51], s[76:77], 2, v[50:51]
	s_lshl_b32 s92, s91, 2
	v_lshl_add_u64 v[50:51], v[50:51], 0, s[92:93]
	s_waitcnt lgkmcnt(0)
	v_add_f32_e32 v48, v48, v49
	global_store_dword v[50:51], v48, off

; #define LAS __attribute__((address_space(3)))
; __device__ __forceinline__ unsigned cvt_pk_bf16(float lo, float hi) { const cvt_f32x2_t v = {lo, hi}; const cvt_bf16x2_t b = __builtin_convertvector(v, cvt_bf16x2_t); return __builtin_bit_cast(unsigned, b); }
; __device__ __forceinline__ float sq4(f32x4 v) { return (v[0] * v[0] + v[1] * v[1]) + (v[2] * v[2] + v[3] * v[3]); }
;     __device__ __forceinline__ void operator()(const f32x4 (&acc)[2][2][4][2], const Unit& u, int wr, int wc, int fr, int fq) const {
;     ...
;             for (int m = 0; m < 4; ++m) {
;                 const int row = u.pm * 256 + ai * 128 + wr * 64 + m * 16 + fr;
;                 const size_t off = (size_t)row * DM + col0;
;                 float ss = 0.f;
; #pragma unroll
;                 for (int bj = 0; bj < 2; ++bj) {
;                     const f32x4 xo0 = xr[m][bj][0] + *(const LAS f32x4*)(gtp + 128 * bj) * acc[ai][bj][m][0], xo1 = xr[m][bj][1] + *(const LAS f32x4*)(gtp + 128 * bj + 4) * acc[ai][bj][m][1];
;                     *(f32x4*)(xout + off + 128 * bj) = xo0; *(f32x4*)(xout + off + 128 * bj + 4) = xo1;
;                     if (gmn) { ss += sq4(xo0) + sq4(xo1); const f32x4 a = xo0 * *(const LAS f32x4*)(gmp + 128 * bj), c = xo1 * *(const LAS f32x4*)(gmp + 128 * bj + 4);
;                         u32x4 w; w.x = cvt_pk_bf16(a[0], a[1]); w.y = cvt_pk_bf16(a[2], a[3]); w.z = cvt_pk_bf16(c[0], c[1]); w.w = cvt_pk_bf16(c[2], c[3]); *(u32x4*)(AX + off + 128 * bj) = w; }
;                 }
;                 if (gmn) { ss += __shfl_xor(ss, 16); ss += __shfl_xor(ss, 32); if (fq == 0) statx[(size_t)row * 16 + u.pn * 4 + wc] = ss; }
.LBB0_353:
	s_waitcnt lgkmcnt(0)
	v_lshlrev_b64 v[48:49], 10, v[132:133]
	v_lshl_add_u64 v[120:121], v[48:49], 0, v[224:225]
	s_waitcnt vmcnt(14)
	v_pk_fma_f32 v[48:49], v[46:47], v[86:87], v[118:119]
	v_pk_fma_f32 v[46:47], v[44:45], v[84:85], v[116:117]
	v_pk_fma_f32 v[52:53], v[42:43], v[78:79], v[114:115]
	v_pk_fma_f32 v[50:51], v[40:41], v[76:77], v[112:113]
	v_lshl_add_u64 v[54:55], v[120:121], 2, s[6:7]
	v_lshl_add_u32 v54, v120, 2, v246
	s_mov_b64 s[54:55], -1
	s_and_b64 vcc, exec, s[46:47]
	s_waitcnt vmcnt(12)
	v_pk_fma_f32 v[44:45], v[36:37], v[60:61], v[108:109]
	v_pk_fma_f32 v[40:41], v[28:29], v[56:57], v[104:105]
	ds_write_b128 v208, v[46:49]
	ds_write_b128 v208, v[50:53] offset:16
	ds_read_b128 v[216:219], v210
	ds_read_b128 v[220:223], v210 offset:1152
	s_cbranch_vccnz .Lxn_pf_9160
	v_mul_f32_e32 v28, v47, v47
	v_mul_f32_e32 v29, v49, v49
	ds_read_b128 v[112:115], v192
	ds_read_b128 v[116:119], v192 offset:16
	v_fmac_f32_e32 v28, v46, v46
	v_fmac_f32_e32 v29, v48, v48
	v_add_f32_e32 v28, v28, v29
	v_mul_f32_e32 v29, v51, v51
	v_mul_f32_e32 v36, v53, v53
	v_fmac_f32_e32 v29, v50, v50
	v_fmac_f32_e32 v36, v52, v52
	v_add_f32_e32 v29, v29, v36
	v_add_f32_e32 v108, v28, v29
	s_waitcnt lgkmcnt(1)
	v_pk_mul_f32 v[28:29], v[48:49], v[114:115]
	v_pk_mul_f32 v[36:37], v[46:47], v[112:113]
	s_waitcnt lgkmcnt(0)
	v_pk_mul_f32 v[42:43], v[52:53], v[118:119]
	v_pk_mul_f32 v[48:49], v[50:51], v[116:117]
	v_cvt_pk_bf16_f32 v46, v36, v37
	v_cvt_pk_bf16_f32 v47, v28, v29
	v_cvt_pk_bf16_f32 v48, v48, v49
	v_cvt_pk_bf16_f32 v49, v42, v43
	v_lshl_add_u64 v[28:29], v[120:121], 1, s[16:17]
	ds_bpermute_b32 v46, v206, v46
	ds_bpermute_b32 v47, v206, v47
	ds_bpermute_b32 v48, v206, v48
	ds_bpermute_b32 v49, v206, v49
	s_waitcnt lgkmcnt(0)
	v_lshl_add_u64 v[28:29], v[204:205], 0, v[28:29]
	global_store_dwordx4 v[28:29], v[46:49], off
	s_waitcnt lgkmcnt(0)
	global_store_dwordx4 v54, v[216:219], s[6:7]
	global_store_dwordx4 v54, v[220:223], s[100:101]
	v_pk_fma_f32 v[42:43], v[30:31], v[58:59], v[106:107]
	s_nop 0
	v_pk_fma_f32 v[46:47], v[38:39], v[62:63], v[110:111]
	ds_write_b128 v208, v[44:47]
	ds_write_b128 v208, v[40:43] offset:16
	ds_read_b128 v[216:219], v210
	ds_read_b128 v[220:223], v210 offset:1152
	ds_read_b128 v[48:51], v192 offset:512
	s_waitcnt lgkmcnt(0)
	v_pk_mul_f32 v[36:37], v[46:47], v[50:51]
	v_pk_mul_f32 v[52:53], v[44:45], v[48:49]
	ds_read_b128 v[48:51], v192 offset:528
	s_waitcnt lgkmcnt(0)
	v_pk_mul_f32 v[104:105], v[42:43], v[50:51]
	v_pk_mul_f32 v[50:51], v[40:41], v[48:49]
	v_cvt_pk_bf16_f32 v48, v52, v53
	v_cvt_pk_bf16_f32 v49, v36, v37
	v_cvt_pk_bf16_f32 v50, v50, v51
	v_cvt_pk_bf16_f32 v51, v104, v105
	ds_bpermute_b32 v48, v206, v48
	ds_bpermute_b32 v49, v206, v49
	ds_bpermute_b32 v50, v206, v50
	ds_bpermute_b32 v51, v206, v51
	s_waitcnt lgkmcnt(0)
	global_store_dwordx4 v[28:29], v[48:51], off offset:256
	s_waitcnt lgkmcnt(0)
	global_store_dwordx4 v54, v[216:219], s[6:7] offset:512
	global_store_dwordx4 v54, v[220:223], s[100:101] offset:512
	v_mul_f32_e32 v28, v45, v45
	v_mul_f32_e32 v29, v47, v47
	v_fmac_f32_e32 v28, v44, v44
	v_fmac_f32_e32 v29, v46, v46
	v_add_f32_e32 v28, v28, v29
	v_mul_f32_e32 v29, v41, v41
	v_mul_f32_e32 v36, v43, v43
	v_fmac_f32_e32 v29, v40, v40
	v_fmac_f32_e32 v36, v42, v42
	v_add_f32_e32 v29, v29, v36
	v_and_b32_e32 v36, 64, v242
	v_add_f32_e32 v28, v28, v29
	v_xor_b32_e32 v29, 16, v242
	v_add_u32_e32 v36, 64, v36
	v_cmp_lt_i32_e32 vcc, v29, v36
	v_add_f32_e32 v28, v108, v28
	s_nop 0
	v_cndmask_b32_e32 v29, v242, v29, vcc
	v_lshlrev_b32_e32 v29, 2, v29
	ds_bpermute_b32 v29, v29, v28
	s_waitcnt lgkmcnt(0)
	v_add_f32_e32 v28, v28, v29
	v_xor_b32_e32 v29, 32, v242
	v_cmp_lt_i32_e32 vcc, v29, v36
	s_nop 1
	v_cndmask_b32_e32 v29, v242, v29, vcc
	v_lshlrev_b32_e32 v29, 2, v29
	ds_bpermute_b32 v29, v29, v28
	s_and_saveexec_b64 s[54:55], s[44:45]
	s_cbranch_execz .LBB0_356
	v_lshlrev_b64 v[36:37], 6, v[132:133]
	v_lshl_add_u64 v[36:37], s[20:21], 0, v[36:37]
	v_lshl_add_u64 v[36:37], s[76:77], 2, v[36:37]
	s_lshl_b32 s92, s91, 2
	v_lshl_add_u64 v[36:37], v[36:37], 0, s[92:93]
	s_waitcnt lgkmcnt(0)
	v_add_f32_e32 v28, v28, v29
	global_store_dword v[36:37], v28, off

; #define LAS __attribute__((address_space(3)))
; __device__ __forceinline__ unsigned cvt_pk_bf16(float lo, float hi) { const cvt_f32x2_t v = {lo, hi}; const cvt_bf16x2_t b = __builtin_convertvector(v, cvt_bf16x2_t); return __builtin_bit_cast(unsigned, b); }
; __device__ __forceinline__ float sq4(f32x4 v) { return (v[0] * v[0] + v[1] * v[1]) + (v[2] * v[2] + v[3] * v[3]); }
;     __device__ __forceinline__ void operator()(const f32x4 (&acc)[2][2][4][2], const Unit& u, int wr, int wc, int fr, int fq) const {
;     ...
;             for (int m = 0; m < 4; ++m) {
;                 const int row = u.pm * 256 + ai * 128 + wr * 64 + m * 16 + fr;
;                 const size_t off = (size_t)row * DM + col0;
;                 float ss = 0.f;
; #pragma unroll
;                 for (int bj = 0; bj < 2; ++bj) {
;                     const f32x4 xo0 = xr[m][bj][0] + *(const LAS f32x4*)(gtp + 128 * bj) * acc[ai][bj][m][0], xo1 = xr[m][bj][1] + *(const LAS f32x4*)(gtp + 128 * bj + 4) * acc[ai][bj][m][1];
;                     *(f32x4*)(xout + off + 128 * bj) = xo0; *(f32x4*)(xout + off + 128 * bj + 4) = xo1;
;                     if (gmn) { ss += sq4(xo0) + sq4(xo1); const f32x4 a = xo0 * *(const LAS f32x4*)(gmp + 128 * bj), c = xo1 * *(const LAS f32x4*)(gmp + 128 * bj + 4);
;                         u32x4 w; w.x = cvt_pk_bf16(a[0], a[1]); w.y = cvt_pk_bf16(a[2], a[3]); w.z = cvt_pk_bf16(c[0], c[1]); w.w = cvt_pk_bf16(c[2], c[3]); *(u32x4*)(AX + off + 128 * bj) = w; }
;                 }
;                 if (gmn) { ss += __shfl_xor(ss, 16); ss += __shfl_xor(ss, 32); if (fq == 0) statx[(size_t)row * 16 + u.pn * 4 + wc] = ss; }
.LBB0_359:
	s_waitcnt lgkmcnt(0)
	v_lshlrev_b64 v[28:29], 10, v[130:131]
	v_lshl_add_u64 v[30:31], v[28:29], 0, v[224:225]
	s_waitcnt vmcnt(12)
	v_pk_fma_f32 v[34:35], v[34:35], v[86:87], v[102:103]
	v_pk_fma_f32 v[32:33], v[32:33], v[84:85], v[100:101]
	v_pk_fma_f32 v[38:39], v[26:27], v[78:79], v[98:99]
	v_pk_fma_f32 v[36:37], v[24:25], v[76:77], v[96:97]
	v_lshl_add_u64 v[40:41], v[30:31], 2, s[6:7]
	v_lshl_add_u32 v40, v30, 2, v246
	s_mov_b64 s[54:55], -1
	s_and_b64 vcc, exec, s[46:47]
	s_waitcnt vmcnt(10)
	v_pk_fma_f32 v[28:29], v[20:21], v[60:61], v[92:93]
	v_pk_fma_f32 v[24:25], v[12:13], v[56:57], v[88:89]
	ds_write_b128 v208, v[32:35]
	ds_write_b128 v208, v[36:39] offset:16
	ds_read_b128 v[216:219], v210
	ds_read_b128 v[220:223], v210 offset:1152
	s_cbranch_vccnz .Lxn_pf_9272
	v_mul_f32_e32 v12, v33, v33
	v_mul_f32_e32 v13, v35, v35
	ds_read_b128 v[42:45], v192
	ds_read_b128 v[46:49], v192 offset:16
	v_fmac_f32_e32 v12, v32, v32
	v_fmac_f32_e32 v13, v34, v34
	v_add_f32_e32 v12, v12, v13
	v_mul_f32_e32 v13, v37, v37
	v_mul_f32_e32 v20, v39, v39
	v_fmac_f32_e32 v13, v36, v36
	v_fmac_f32_e32 v20, v38, v38
	v_add_f32_e32 v13, v13, v20
	v_add_f32_e32 v50, v12, v13
	s_waitcnt lgkmcnt(1)
	v_pk_mul_f32 v[12:13], v[34:35], v[44:45]
	v_pk_mul_f32 v[20:21], v[32:33], v[42:43]
	s_waitcnt lgkmcnt(0)
	v_pk_mul_f32 v[26:27], v[38:39], v[48:49]
	v_pk_mul_f32 v[34:35], v[36:37], v[46:47]
	v_cvt_pk_bf16_f32 v32, v20, v21
	v_cvt_pk_bf16_f32 v33, v12, v13
	v_cvt_pk_bf16_f32 v34, v34, v35
	v_cvt_pk_bf16_f32 v35, v26, v27
	v_lshl_add_u64 v[12:13], v[30:31], 1, s[16:17]
	v_lshl_add_u64 v[12:13], v[204:205], 0, v[12:13]
	v_pk_fma_f32 v[30:31], v[22:23], v[62:63], v[94:95]
	ds_bpermute_b32 v32, v206, v32
	ds_bpermute_b32 v33, v206, v33
	ds_bpermute_b32 v34, v206, v34
	ds_bpermute_b32 v35, v206, v35
	s_waitcnt lgkmcnt(0)
	global_store_dwordx4 v[12:13], v[32:35], off
	s_waitcnt lgkmcnt(0)
	global_store_dwordx4 v40, v[216:219], s[6:7]
	global_store_dwordx4 v40, v[220:223], s[100:101]
	v_pk_fma_f32 v[26:27], v[14:15], v[58:59], v[90:91]
	ds_write_b128 v208, v[28:31]
	ds_write_b128 v208, v[24:27] offset:16
	ds_read_b128 v[216:219], v210
	ds_read_b128 v[220:223], v210 offset:1152
	ds_read_b128 v[32:35], v192 offset:512
	s_waitcnt lgkmcnt(0)
	v_pk_mul_f32 v[20:21], v[30:31], v[34:35]
	v_pk_mul_f32 v[36:37], v[28:29], v[32:33]
	ds_read_b128 v[32:35], v192 offset:528
	s_waitcnt lgkmcnt(0)
	v_pk_mul_f32 v[38:39], v[26:27], v[34:35]
	v_pk_mul_f32 v[34:35], v[24:25], v[32:33]
	v_cvt_pk_bf16_f32 v32, v36, v37
	v_cvt_pk_bf16_f32 v33, v20, v21
	v_cvt_pk_bf16_f32 v34, v34, v35
	v_cvt_pk_bf16_f32 v35, v38, v39
	ds_bpermute_b32 v32, v206, v32
	ds_bpermute_b32 v33, v206, v33
	ds_bpermute_b32 v34, v206, v34
	ds_bpermute_b32 v35, v206, v35
	s_waitcnt lgkmcnt(0)
	global_store_dwordx4 v[12:13], v[32:35], off offset:256
	s_waitcnt lgkmcnt(0)
	global_store_dwordx4 v40, v[216:219], s[6:7] offset:512
	global_store_dwordx4 v40, v[220:223], s[100:101] offset:512
	v_mul_f32_e32 v12, v29, v29
	v_mul_f32_e32 v13, v31, v31
	v_fmac_f32_e32 v12, v28, v28
	v_fmac_f32_e32 v13, v30, v30
	v_add_f32_e32 v12, v12, v13
	v_mul_f32_e32 v13, v25, v25
	v_mul_f32_e32 v20, v27, v27
	v_fmac_f32_e32 v13, v24, v24
	v_fmac_f32_e32 v20, v26, v26
	v_add_f32_e32 v13, v13, v20
	v_and_b32_e32 v20, 64, v242
	v_add_f32_e32 v12, v12, v13
	v_xor_b32_e32 v13, 16, v242
	v_add_u32_e32 v20, 64, v20
	v_cmp_lt_i32_e32 vcc, v13, v20
	v_add_f32_e32 v12, v50, v12
	s_nop 0
	v_cndmask_b32_e32 v13, v242, v13, vcc
	v_lshlrev_b32_e32 v13, 2, v13
	ds_bpermute_b32 v13, v13, v12
	s_waitcnt lgkmcnt(0)
	v_add_f32_e32 v12, v12, v13
	v_xor_b32_e32 v13, 32, v242
	v_cmp_lt_i32_e32 vcc, v13, v20
	s_nop 1
	v_cndmask_b32_e32 v13, v242, v13, vcc
	v_lshlrev_b32_e32 v13, 2, v13
	ds_bpermute_b32 v13, v13, v12
	s_and_saveexec_b64 s[54:55], s[44:45]
	s_cbranch_execz .LBB0_362
	v_lshlrev_b64 v[20:21], 6, v[130:131]
	v_lshl_add_u64 v[20:21], s[20:21], 0, v[20:21]
	v_lshl_add_u64 v[20:21], s[76:77], 2, v[20:21]
	s_lshl_b32 s92, s91, 2
	v_lshl_add_u64 v[20:21], v[20:21], 0, s[92:93]
	s_waitcnt lgkmcnt(0)
	v_add_f32_e32 v12, v12, v13
	global_store_dword v[20:21], v12, off

; #define LAS __attribute__((address_space(3)))
;     __device__ __forceinline__ void operator()(const f32x4 (&acc)[2][2][4][2], const Unit& u, int wr, int wc, int fr, int fq) const {
;     ...
;                     const f32x4 xo0 = xr[m][bj][0] + *(const LAS f32x4*)(gtp + 128 * bj) * acc[ai][bj][m][0], xo1 = xr[m][bj][1] + *(const LAS f32x4*)(gtp + 128 * bj + 4) * acc[ai][bj][m][1];
;                     *(f32x4*)(xout + off + 128 * bj) = xo0; *(f32x4*)(xout + off + 128 * bj + 4) = xo1;
.Lxn_pf_8564:
	s_waitcnt lgkmcnt(0)
	global_store_dwordx4 v236, v[216:219], s[6:7]
	global_store_dwordx4 v236, v[220:223], s[100:101]
	s_branch .LBB0_325
.Lxn_pf_8611:
	s_waitcnt lgkmcnt(0)
	global_store_dwordx4 v236, v[216:219], s[6:7] offset:512
	global_store_dwordx4 v236, v[220:223], s[100:101] offset:512
	s_branch .LBB0_329
.Lxn_pf_8680:
	s_waitcnt lgkmcnt(0)
	global_store_dwordx4 v126, v[216:219], s[6:7]
	global_store_dwordx4 v126, v[220:223], s[100:101]
	s_branch .LBB0_333
.Lxn_pf_8790:
	s_waitcnt lgkmcnt(0)
	global_store_dwordx4 v108, v[216:219], s[6:7]
	global_store_dwordx4 v108, v[220:223], s[100:101]
	s_branch .LBB0_339
.Lxn_pf_8899:
	s_waitcnt lgkmcnt(0)
	global_store_dwordx4 v88, v[216:219], s[6:7]
	global_store_dwordx4 v88, v[220:223], s[100:101]
	s_branch .LBB0_345
.Lxn_pf_9046:
	s_waitcnt lgkmcnt(0)
	global_store_dwordx4 v136, v[216:219], s[6:7]
	global_store_dwordx4 v136, v[220:223], s[100:101]
	s_branch .LBB0_349
.Lxn_pf_9089:
	s_waitcnt lgkmcnt(0)
	global_store_dwordx4 v136, v[216:219], s[6:7] offset:512
	global_store_dwordx4 v136, v[220:223], s[100:101] offset:512
	s_branch .LBB0_353
.Lxn_pf_9160:
	s_waitcnt lgkmcnt(0)
	global_store_dwordx4 v54, v[216:219], s[6:7]
	global_store_dwordx4 v54, v[220:223], s[100:101]
	s_branch .LBB0_357
.Lxn_pf_9272:
	s_waitcnt lgkmcnt(0)
	global_store_dwordx4 v40, v[216:219], s[6:7]
	global_store_dwordx4 v40, v[220:223], s[100:101]
	s_branch .LBB0_363

; #define LAS __attribute__((address_space(3)))
; __device__ __forceinline__ unsigned cvt_pk_bf16(float lo, float hi) { const cvt_f32x2_t v = {lo, hi}; const cvt_bf16x2_t b = __builtin_convertvector(v, cvt_bf16x2_t); return __builtin_bit_cast(unsigned, b); }
; __device__ __forceinline__ float sq4(f32x4 v) { return (v[0] * v[0] + v[1] * v[1]) + (v[2] * v[2] + v[3] * v[3]); }
;     __device__ __forceinline__ void operator()(const f32x4 (&acc)[2][2][4][2], const Unit& u, int wr, int wc, int fr, int fq) const {
;     ...
;             for (int m = 0; m < 4; ++m) {
;                 const int row = u.pm * 256 + ai * 128 + wr * 64 + m * 16 + fr;
;                 const size_t off = (size_t)row * DM + col0;
;                 float ss = 0.f;
; #pragma unroll
;                 for (int bj = 0; bj < 2; ++bj) {
;                     const f32x4 xo0 = xr[m][bj][0] + *(const LAS f32x4*)(gtp + 128 * bj) * acc[ai][bj][m][0], xo1 = xr[m][bj][1] + *(const LAS f32x4*)(gtp + 128 * bj + 4) * acc[ai][bj][m][1];
;                     *(f32x4*)(xout + off + 128 * bj) = xo0; *(f32x4*)(xout + off + 128 * bj + 4) = xo1;
;                     if (gmn) { ss += sq4(xo0) + sq4(xo1); const f32x4 a = xo0 * *(const LAS f32x4*)(gmp + 128 * bj), c = xo1 * *(const LAS f32x4*)(gmp + 128 * bj + 4);
;                         u32x4 w; w.x = cvt_pk_bf16(a[0], a[1]); w.y = cvt_pk_bf16(a[2], a[3]); w.z = cvt_pk_bf16(c[0], c[1]); w.w = cvt_pk_bf16(c[2], c[3]); *(u32x4*)(AX + off + 128 * bj) = w; }
;                 }
;                 if (gmn) { ss += __shfl_xor(ss, 16); ss += __shfl_xor(ss, 32); if (fq == 0) statx[(size_t)row * 16 + u.pn * 4 + wc] = ss; }
.LBB0_372:
	v_mul_f32_e32 v0, v17, v17
	v_mul_f32_e32 v1, v19, v19
	ds_read_b128 v[26:29], v192
	ds_read_b128 v[30:33], v192 offset:16
	v_fmac_f32_e32 v0, v16, v16
	v_fmac_f32_e32 v1, v18, v18
	v_add_f32_e32 v0, v0, v1
	v_mul_f32_e32 v1, v21, v21
	v_mul_f32_e32 v4, v23, v23
	v_fmac_f32_e32 v1, v20, v20
	v_fmac_f32_e32 v4, v22, v22
	v_add_f32_e32 v1, v1, v4
	v_add_f32_e32 v34, v0, v1
	s_waitcnt lgkmcnt(1)
	v_pk_mul_f32 v[0:1], v[18:19], v[28:29]
	v_pk_mul_f32 v[4:5], v[16:17], v[26:27]
	s_waitcnt lgkmcnt(0)
	v_pk_mul_f32 v[10:11], v[22:23], v[32:33]
	v_pk_mul_f32 v[18:19], v[20:21], v[30:31]
	v_cvt_pk_bf16_f32 v16, v4, v5
	v_cvt_pk_bf16_f32 v17, v0, v1
	v_cvt_pk_bf16_f32 v18, v18, v19
	v_cvt_pk_bf16_f32 v19, v10, v11
	v_lshl_add_u64 v[0:1], v[14:15], 1, s[16:17]
	v_lshl_add_u64 v[0:1], v[204:205], 0, v[0:1]
	v_pk_fma_f32 v[14:15], v[6:7], v[62:63], v[70:71]
	ds_bpermute_b32 v16, v206, v16
	ds_bpermute_b32 v17, v206, v17
	ds_bpermute_b32 v18, v206, v18
	ds_bpermute_b32 v19, v206, v19
	s_waitcnt lgkmcnt(0)
	global_store_dwordx4 v[0:1], v[16:19], off
	v_pk_fma_f32 v[10:11], v[2:3], v[58:59], v[66:67]
	ds_write_b128 v208, v[12:15]
	ds_write_b128 v208, v[8:11] offset:16
	ds_read_b128 v[216:219], v210
	ds_read_b128 v[220:223], v210 offset:1152
	ds_read_b128 v[16:19], v192 offset:512
	s_waitcnt lgkmcnt(0)
	v_pk_mul_f32 v[4:5], v[14:15], v[18:19]
	v_pk_mul_f32 v[20:21], v[12:13], v[16:17]
	ds_read_b128 v[16:19], v192 offset:528
	s_waitcnt lgkmcnt(0)
	v_pk_mul_f32 v[22:23], v[10:11], v[18:19]
	v_pk_mul_f32 v[18:19], v[8:9], v[16:17]
	v_cvt_pk_bf16_f32 v16, v20, v21
	v_cvt_pk_bf16_f32 v17, v4, v5
	v_cvt_pk_bf16_f32 v18, v18, v19
	v_cvt_pk_bf16_f32 v19, v22, v23
	ds_bpermute_b32 v16, v206, v16
	ds_bpermute_b32 v17, v206, v17
	ds_bpermute_b32 v18, v206, v18
	ds_bpermute_b32 v19, v206, v19
	s_waitcnt lgkmcnt(0)
	global_store_dwordx4 v[0:1], v[16:19], off offset:256
	s_waitcnt lgkmcnt(0)
	global_store_dwordx4 v24, v[216:219], s[6:7] offset:512
	global_store_dwordx4 v24, v[220:223], s[100:101] offset:512
	v_mul_f32_e32 v0, v13, v13
	v_mul_f32_e32 v1, v15, v15
	v_fmac_f32_e32 v0, v12, v12
	v_fmac_f32_e32 v1, v14, v14
	v_add_f32_e32 v0, v0, v1
	v_mul_f32_e32 v1, v9, v9
	v_mul_f32_e32 v4, v11, v11
	v_fmac_f32_e32 v1, v8, v8
	v_fmac_f32_e32 v4, v10, v10
	v_add_f32_e32 v1, v1, v4
	v_and_b32_e32 v4, 64, v242
	v_add_f32_e32 v0, v0, v1
	v_xor_b32_e32 v1, 16, v242
	v_add_u32_e32 v4, 64, v4
	v_cmp_lt_i32_e32 vcc, v1, v4
	v_add_f32_e32 v0, v34, v0
	s_nop 0
	v_cndmask_b32_e32 v1, v242, v1, vcc
	v_lshlrev_b32_e32 v1, 2, v1
	ds_bpermute_b32 v1, v1, v0
	s_waitcnt lgkmcnt(0)
	v_add_f32_e32 v0, v0, v1
	v_xor_b32_e32 v1, 32, v242
	v_cmp_lt_i32_e32 vcc, v1, v4
	s_nop 1
	v_cndmask_b32_e32 v1, v242, v1, vcc
	v_lshlrev_b32_e32 v1, 2, v1
	ds_bpermute_b32 v1, v1, v0
	s_and_saveexec_b64 s[46:47], s[44:45]
	s_cbranch_execz .LBB0_374
	v_lshlrev_b64 v[4:5], 6, v[128:129]
	v_lshl_add_u64 v[4:5], s[20:21], 0, v[4:5]
	v_lshl_add_u64 v[4:5], s[76:77], 2, v[4:5]
	s_lshl_b32 s92, s91, 2
	v_lshl_add_u64 v[4:5], v[4:5], 0, s[92:93]
	s_waitcnt lgkmcnt(0)
	v_add_f32_e32 v0, v0, v1
	global_store_dword v[4:5], v0, off
